# batched/pipelined gate loads in branch-merge GEMM epilogue; counted vmcnt in NSA sel/win loops; s40 temp in residual epilogue
# speedup vs baseline: 1.0369x; 1.0104x over previous
; __device__ __forceinline__ unsigned cvt_pk(float lo, float hi) { f32x2_t v = {lo, hi}; bf16x2_t b = __builtin_convertvector(v, bf16x2_t); return __builtin_bit_cast(unsigned, b); }
;     __device__ __forceinline__ bool carry(f32x4 (&acc)[2][2][4][2], const Unit& u, int wr, int wc, int fr, int fq) const {
;         const int br = u.pn >> 2, pm = u.pm - 128 * br, pn = u.pn & 3;
;         const int row0 = pm * 256 + wr * 64 + fr, col0 = pn * 256 + wc * 32 + 8 * fq;
; #pragma unroll
;         for (int ai = 0; ai < 2; ++ai)
; #pragma unroll
;             for (int m = 0; m < 4; ++m)
; #pragma unroll
;                 for (int bj = 0; bj < 2; ++bj) {
;                     const size_t row = (size_t)(row0 + ai * 128 + m * 16); const int c = col0 + bj * 128;
;                     const u32x4 gn = *(const u32x4*)(G + row * (3 * DM) + br * DM + c);
;                     float f[8];
; #pragma unroll
;                     for (int j = 0; j < 4; ++j) { f[2 * j] = __uint_as_float(gn[j] << 16); f[2 * j + 1] = __uint_as_float(gn[j] & 0xffff0000u); }
;                     if (br < 2) {
;                         const u32x4 gd = *(const u32x4*)(G + row * (3 * DM) + (br + 1) * DM + c);
; #pragma unroll
;                         for (int j = 0; j < 4; ++j) {
;                             f[2 * j] *= __builtin_amdgcn_rcpf(fmaxf(__uint_as_float(gd[j] << 16), 1e-30f));
;                             f[2 * j + 1] *= __builtin_amdgcn_rcpf(fmaxf(__uint_as_float(gd[j] & 0xffff0000u), 1e-30f));
;                         }
; #pragma unroll
;                         for (int i = 0; i < 8; ++i) acc[ai][bj][m][i >> 2][i & 3] *= f[i];
;                     } else {
;                         float v[8];
; #pragma unroll
;                         for (int i = 0; i < 8; ++i) v[i] = acc[ai][bj][m][i >> 2][i & 3] * f[i];
;                         u32x4 w; w.x = cvt_pk(v[0], v[1]); w.y = cvt_pk(v[2], v[3]); w.z = cvt_pk(v[4], v[5]); w.w = cvt_pk(v[6], v[7]);
;                         *(u32x4*)(Mg + row * DM + c) = w;
;                     }
;                 }
;         return br < 2;
.LBB0_40:
	s_ashr_i32 s13, s40, 2
	s_lshl_b32 s6, s13, 15
	v_subrev_u32_e32 v0, s6, v156
	v_lshl_add_u32 v2, s48, 8, v0
	s_lshl_b32 s6, s40, 8
	s_and_b32 s6, s6, 0x300
	v_or_b32_e32 v0, s6, v158
	v_readlane_b32 s24, v252, 37
	v_readlane_b32 s25, v252, 38
	v_readlane_b32 s52, v255, 9
	v_readlane_b32 s53, v255, 10
	v_mov_b32_e32 v224, 0x3ecc95a3
	v_lshlrev_b32_e32 v0, 1, v0
	v_mov_b32_e32 v3, 0x1800
	v_mul_u32_u24_e32 v182, v2, v3
	s_lshl_b32 s48, s13, 11
	v_add3_u32 v182, v182, v0, s48
	v_lshl_add_u32 v186, v2, 11, v0
	v_add_u32_e32 v183, 0x18000, v182
	v_add_u32_e32 v187, 0x8000, v186
	v_add_u32_e32 v184, 0x30000, v182
	v_add_u32_e32 v188, 0x10000, v186
	v_add_u32_e32 v185, 0x48000, v182
	v_add_u32_e32 v189, 0x18000, v186
	s_add_u32 s98, s24, 0xc0000
	s_addc_u32 s99, s25, 0
	s_add_u32 s100, s72, 0x40000
	s_addc_u32 s101, s73, 0
	s_cmp_gt_i32 s13, 1
	s_cselect_b64 s[40:41], 0, -1
	s_cbranch_scc1 .Lmg_final
	global_load_dwordx4 v[194:197], v182, s[24:25]
	global_load_dwordx4 v[198:201], v182, s[24:25] offset:2048
	global_load_dwordx4 v[202:205], v182, s[24:25] offset:256
	global_load_dwordx4 v[206:209], v182, s[24:25] offset:2304
	global_load_dwordx4 v[210:213], v183, s[24:25]
	global_load_dwordx4 v[226:229], v183, s[24:25] offset:2048
	global_load_dwordx4 v[230:233], v183, s[24:25] offset:256
	global_load_dwordx4 v[234:237], v183, s[24:25] offset:2304
	global_load_dwordx4 v[238:241], v184, s[24:25]
	global_load_dwordx4 v[242:245], v184, s[24:25] offset:2048
	s_waitcnt vmcnt(8)
	v_lshlrev_b32_e32 v144, 16, v198
	v_and_b32_e32 v145, 0xffff0000, v198
	v_lshlrev_b32_e32 v146, 16, v199
	v_and_b32_e32 v147, 0xffff0000, v199
	v_lshlrev_b32_e32 v148, 16, v200
	v_and_b32_e32 v149, 0xffff0000, v200
	v_lshlrev_b32_e32 v150, 16, v201
	v_and_b32_e32 v151, 0xffff0000, v201
	v_lshlrev_b32_e32 v152, 16, v194
	v_and_b32_e32 v153, 0xffff0000, v194
	v_lshlrev_b32_e32 v154, 16, v195
	v_and_b32_e32 v155, 0xffff0000, v195
	v_lshlrev_b32_e32 v190, 16, v196
	v_and_b32_e32 v191, 0xffff0000, v196
	v_lshlrev_b32_e32 v2, 16, v197
	v_and_b32_e32 v3, 0xffff0000, v197
	global_load_dwordx4 v[194:197], v184, s[24:25] offset:256
	global_load_dwordx4 v[198:201], v184, s[24:25] offset:2304
	v_max_f32_e32 v144, v144, v144
	v_max_f32_e32 v145, v145, v145
	v_max_f32_e32 v146, v146, v146
	v_max_f32_e32 v147, v147, v147
	v_max_f32_e32 v148, v148, v148
	v_max_f32_e32 v149, v149, v149
	v_max_f32_e32 v150, v150, v150
	v_max_f32_e32 v151, v151, v151
	v_max_f32_e32 v144, 0xda24260, v144
	v_max_f32_e32 v145, 0xda24260, v145
	v_max_f32_e32 v146, 0xda24260, v146
	v_max_f32_e32 v147, 0xda24260, v147
	v_max_f32_e32 v148, 0xda24260, v148
	v_max_f32_e32 v149, 0xda24260, v149
	v_max_f32_e32 v150, 0xda24260, v150
	v_max_f32_e32 v151, 0xda24260, v151
	v_rcp_f32_e32 v144, v144
	v_rcp_f32_e32 v145, v145
	v_rcp_f32_e32 v146, v146
	v_rcp_f32_e32 v147, v147
	v_rcp_f32_e32 v148, v148
	v_rcp_f32_e32 v149, v149
	v_rcp_f32_e32 v150, v150
	v_rcp_f32_e32 v151, v151
	s_nop 0
	v_pk_mul_f32 v[152:153], v[144:145], v[152:153]
	v_pk_mul_f32 v[154:155], v[146:147], v[154:155]
	v_pk_mul_f32 v[190:191], v[148:149], v[190:191]
	v_pk_mul_f32 v[2:3], v[150:151], v[2:3]
	v_pk_mul_f32 v[128:129], v[128:129], v[152:153]
	v_pk_mul_f32 v[130:131], v[130:131], v[154:155]
	v_pk_mul_f32 v[124:125], v[124:125], v[190:191]
	v_pk_mul_f32 v[126:127], v[126:127], v[2:3]
	s_waitcnt vmcnt(8)
	v_lshlrev_b32_e32 v144, 16, v206
	v_and_b32_e32 v145, 0xffff0000, v206
	v_lshlrev_b32_e32 v146, 16, v207
	v_and_b32_e32 v147, 0xffff0000, v207
	v_lshlrev_b32_e32 v148, 16, v208
	v_and_b32_e32 v149, 0xffff0000, v208
	v_lshlrev_b32_e32 v150, 16, v209
	v_and_b32_e32 v151, 0xffff0000, v209
	v_lshlrev_b32_e32 v152, 16, v202
	v_and_b32_e32 v153, 0xffff0000, v202
	v_lshlrev_b32_e32 v154, 16, v203
	v_and_b32_e32 v155, 0xffff0000, v203
	v_lshlrev_b32_e32 v190, 16, v204
	v_and_b32_e32 v191, 0xffff0000, v204
	v_lshlrev_b32_e32 v2, 16, v205
	v_and_b32_e32 v3, 0xffff0000, v205
	global_load_dwordx4 v[202:205], v185, s[24:25]
	global_load_dwordx4 v[206:209], v185, s[24:25] offset:2048
	v_max_f32_e32 v144, v144, v144
	v_max_f32_e32 v145, v145, v145
	v_max_f32_e32 v146, v146, v146
	v_max_f32_e32 v147, v147, v147
	v_max_f32_e32 v148, v148, v148
	v_max_f32_e32 v149, v149, v149
	v_max_f32_e32 v150, v150, v150
	v_max_f32_e32 v151, v151, v151
	v_max_f32_e32 v144, 0xda24260, v144
	v_max_f32_e32 v145, 0xda24260, v145
	v_max_f32_e32 v146, 0xda24260, v146
	v_max_f32_e32 v147, 0xda24260, v147
	v_max_f32_e32 v148, 0xda24260, v148
	v_max_f32_e32 v149, 0xda24260, v149
	v_max_f32_e32 v150, 0xda24260, v150
	v_max_f32_e32 v151, 0xda24260, v151
	v_rcp_f32_e32 v144, v144
	v_rcp_f32_e32 v145, v145
	v_rcp_f32_e32 v146, v146
	v_rcp_f32_e32 v147, v147
	v_rcp_f32_e32 v148, v148
	v_rcp_f32_e32 v149, v149
	v_rcp_f32_e32 v150, v150
	v_rcp_f32_e32 v151, v151
	s_nop 0
	v_pk_mul_f32 v[152:153], v[144:145], v[152:153]
	v_pk_mul_f32 v[154:155], v[146:147], v[154:155]
	v_pk_mul_f32 v[190:191], v[148:149], v[190:191]
	v_pk_mul_f32 v[2:3], v[150:151], v[2:3]
	v_pk_mul_f32 v[96:97], v[96:97], v[152:153]
	v_pk_mul_f32 v[98:99], v[98:99], v[154:155]
	v_pk_mul_f32 v[92:93], v[92:93], v[190:191]
	v_pk_mul_f32 v[94:95], v[94:95], v[2:3]
	s_waitcnt vmcnt(8)
;     __device__ __forceinline__ bool carry(f32x4 (&acc)[2][2][4][2], const Unit& u, int wr, int wc, int fr, int fq) const {
;     ...
;                     const size_t row = (size_t)(row0 + ai * 128 + m * 16); const int c = col0 + bj * 128;
;                     const u32x4 gn = *(const u32x4*)(G + row * (3 * DM) + br * DM + c);
;                     float f[8];
; #pragma unroll
;                     for (int j = 0; j < 4; ++j) { f[2 * j] = __uint_as_float(gn[j] << 16); f[2 * j + 1] = __uint_as_float(gn[j] & 0xffff0000u); }
;                     if (br < 2) {
;                         const u32x4 gd = *(const u32x4*)(G + row * (3 * DM) + (br + 1) * DM + c);
; #pragma unroll
;                         for (int j = 0; j < 4; ++j) {
;                             f[2 * j] *= __builtin_amdgcn_rcpf(fmaxf(__uint_as_float(gd[j] << 16), 1e-30f));
;                             f[2 * j + 1] *= __builtin_amdgcn_rcpf(fmaxf(__uint_as_float(gd[j] & 0xffff0000u), 1e-30f));
;                         }
; #pragma unroll
;                         for (int i = 0; i < 8; ++i) acc[ai][bj][m][i >> 2][i & 3] *= f[i];
	v_lshlrev_b32_e32 v144, 16, v226
	v_and_b32_e32 v145, 0xffff0000, v226
	v_lshlrev_b32_e32 v146, 16, v227
	v_and_b32_e32 v147, 0xffff0000, v227
	v_lshlrev_b32_e32 v148, 16, v228
	v_and_b32_e32 v149, 0xffff0000, v228
	v_lshlrev_b32_e32 v150, 16, v229
	v_and_b32_e32 v151, 0xffff0000, v229
	v_lshlrev_b32_e32 v152, 16, v210
	v_and_b32_e32 v153, 0xffff0000, v210
	v_lshlrev_b32_e32 v154, 16, v211
	v_and_b32_e32 v155, 0xffff0000, v211
	v_lshlrev_b32_e32 v190, 16, v212
	v_and_b32_e32 v191, 0xffff0000, v212
	v_lshlrev_b32_e32 v2, 16, v213
	v_and_b32_e32 v3, 0xffff0000, v213
	global_load_dwordx4 v[210:213], v185, s[24:25] offset:256
	global_load_dwordx4 v[226:229], v185, s[24:25] offset:2304
	v_max_f32_e32 v144, v144, v144
	v_max_f32_e32 v145, v145, v145
	v_max_f32_e32 v146, v146, v146
	v_max_f32_e32 v147, v147, v147
	v_max_f32_e32 v148, v148, v148
	v_max_f32_e32 v149, v149, v149
	v_max_f32_e32 v150, v150, v150
	v_max_f32_e32 v151, v151, v151
	v_max_f32_e32 v144, 0xda24260, v144
	v_max_f32_e32 v145, 0xda24260, v145
	v_max_f32_e32 v146, 0xda24260, v146
	v_max_f32_e32 v147, 0xda24260, v147
	v_max_f32_e32 v148, 0xda24260, v148
	v_max_f32_e32 v149, 0xda24260, v149
	v_max_f32_e32 v150, 0xda24260, v150
	v_max_f32_e32 v151, 0xda24260, v151
	v_rcp_f32_e32 v144, v144
	v_rcp_f32_e32 v145, v145
	v_rcp_f32_e32 v146, v146
	v_rcp_f32_e32 v147, v147
	v_rcp_f32_e32 v148, v148
	v_rcp_f32_e32 v149, v149
	v_rcp_f32_e32 v150, v150
	v_rcp_f32_e32 v151, v151
	s_nop 0
	v_pk_mul_f32 v[152:153], v[144:145], v[152:153]
	v_pk_mul_f32 v[154:155], v[146:147], v[154:155]
	v_pk_mul_f32 v[190:191], v[148:149], v[190:191]
	v_pk_mul_f32 v[2:3], v[150:151], v[2:3]
	v_pk_mul_f32 v[120:121], v[120:121], v[152:153]
	v_pk_mul_f32 v[122:123], v[122:123], v[154:155]
	v_pk_mul_f32 v[116:117], v[116:117], v[190:191]
	v_pk_mul_f32 v[118:119], v[118:119], v[2:3]
	s_waitcnt vmcnt(8)
	v_lshlrev_b32_e32 v144, 16, v234
	v_and_b32_e32 v145, 0xffff0000, v234
	v_lshlrev_b32_e32 v146, 16, v235
	v_and_b32_e32 v147, 0xffff0000, v235
	v_lshlrev_b32_e32 v148, 16, v236
	v_and_b32_e32 v149, 0xffff0000, v236
	v_lshlrev_b32_e32 v150, 16, v237
	v_and_b32_e32 v151, 0xffff0000, v237
	v_lshlrev_b32_e32 v152, 16, v230
	v_and_b32_e32 v153, 0xffff0000, v230
	v_lshlrev_b32_e32 v154, 16, v231
	v_and_b32_e32 v155, 0xffff0000, v231
	v_lshlrev_b32_e32 v190, 16, v232
	v_and_b32_e32 v191, 0xffff0000, v232
	v_lshlrev_b32_e32 v2, 16, v233
	v_and_b32_e32 v3, 0xffff0000, v233
	global_load_dwordx4 v[230:233], v182, s[98:99]
	global_load_dwordx4 v[234:237], v182, s[98:99] offset:2048
	v_max_f32_e32 v144, v144, v144
	v_max_f32_e32 v145, v145, v145
	v_max_f32_e32 v146, v146, v146
	v_max_f32_e32 v147, v147, v147
	v_max_f32_e32 v148, v148, v148
	v_max_f32_e32 v149, v149, v149
	v_max_f32_e32 v150, v150, v150
	v_max_f32_e32 v151, v151, v151
	v_max_f32_e32 v144, 0xda24260, v144
	v_max_f32_e32 v145, 0xda24260, v145
	v_max_f32_e32 v146, 0xda24260, v146
	v_max_f32_e32 v147, 0xda24260, v147
	v_max_f32_e32 v148, 0xda24260, v148
	v_max_f32_e32 v149, 0xda24260, v149
	v_max_f32_e32 v150, 0xda24260, v150
	v_max_f32_e32 v151, 0xda24260, v151
	v_rcp_f32_e32 v144, v144
	v_rcp_f32_e32 v145, v145
	v_rcp_f32_e32 v146, v146
	v_rcp_f32_e32 v147, v147
	v_rcp_f32_e32 v148, v148
	v_rcp_f32_e32 v149, v149
	v_rcp_f32_e32 v150, v150
	v_rcp_f32_e32 v151, v151
	s_nop 0
	v_pk_mul_f32 v[152:153], v[144:145], v[152:153]
	v_pk_mul_f32 v[154:155], v[146:147], v[154:155]
	v_pk_mul_f32 v[190:191], v[148:149], v[190:191]
	v_pk_mul_f32 v[2:3], v[150:151], v[2:3]
	v_pk_mul_f32 v[88:89], v[88:89], v[152:153]
	v_pk_mul_f32 v[90:91], v[90:91], v[154:155]
	v_pk_mul_f32 v[84:85], v[84:85], v[190:191]
	v_pk_mul_f32 v[86:87], v[86:87], v[2:3]
	s_waitcnt vmcnt(8)
	v_lshlrev_b32_e32 v144, 16, v242
	v_and_b32_e32 v145, 0xffff0000, v242
	v_lshlrev_b32_e32 v146, 16, v243
	v_and_b32_e32 v147, 0xffff0000, v243
	v_lshlrev_b32_e32 v148, 16, v244
	v_and_b32_e32 v149, 0xffff0000, v244
	v_lshlrev_b32_e32 v150, 16, v245
	v_and_b32_e32 v151, 0xffff0000, v245
	v_lshlrev_b32_e32 v152, 16, v238
	v_and_b32_e32 v153, 0xffff0000, v238
	v_lshlrev_b32_e32 v154, 16, v239
	v_and_b32_e32 v155, 0xffff0000, v239
	v_lshlrev_b32_e32 v190, 16, v240
	v_and_b32_e32 v191, 0xffff0000, v240
	v_lshlrev_b32_e32 v2, 16, v241
	v_and_b32_e32 v3, 0xffff0000, v241
	global_load_dwordx4 v[238:241], v182, s[98:99] offset:256
	global_load_dwordx4 v[242:245], v182, s[98:99] offset:2304
	v_max_f32_e32 v144, v144, v144
	v_max_f32_e32 v145, v145, v145
	v_max_f32_e32 v146, v146, v146
	v_max_f32_e32 v147, v147, v147
	v_max_f32_e32 v148, v148, v148
	v_max_f32_e32 v149, v149, v149
	v_max_f32_e32 v150, v150, v150
	v_max_f32_e32 v151, v151, v151
	v_max_f32_e32 v144, 0xda24260, v144
	v_max_f32_e32 v145, 0xda24260, v145
	v_max_f32_e32 v146, 0xda24260, v146
	v_max_f32_e32 v147, 0xda24260, v147
	v_max_f32_e32 v148, 0xda24260, v148
	v_max_f32_e32 v149, 0xda24260, v149
	v_max_f32_e32 v150, 0xda24260, v150
	v_max_f32_e32 v151, 0xda24260, v151
	v_rcp_f32_e32 v144, v144
	v_rcp_f32_e32 v145, v145
	v_rcp_f32_e32 v146, v146
	v_rcp_f32_e32 v147, v147
	v_rcp_f32_e32 v148, v148
	v_rcp_f32_e32 v149, v149
	v_rcp_f32_e32 v150, v150
	v_rcp_f32_e32 v151, v151
	s_nop 0
	v_pk_mul_f32 v[152:153], v[144:145], v[152:153]
	v_pk_mul_f32 v[154:155], v[146:147], v[154:155]
	v_pk_mul_f32 v[190:191], v[148:149], v[190:191]
	v_pk_mul_f32 v[2:3], v[150:151], v[2:3]
	v_pk_mul_f32 v[112:113], v[112:113], v[152:153]
	v_pk_mul_f32 v[114:115], v[114:115], v[154:155]
	v_pk_mul_f32 v[108:109], v[108:109], v[190:191]
	v_pk_mul_f32 v[110:111], v[110:111], v[2:3]
	s_waitcnt vmcnt(8)
;     __device__ __forceinline__ bool carry(f32x4 (&acc)[2][2][4][2], const Unit& u, int wr, int wc, int fr, int fq) const {
;     ...
;                     const size_t row = (size_t)(row0 + ai * 128 + m * 16); const int c = col0 + bj * 128;
;                     const u32x4 gn = *(const u32x4*)(G + row * (3 * DM) + br * DM + c);
;                     float f[8];
; #pragma unroll
;                     for (int j = 0; j < 4; ++j) { f[2 * j] = __uint_as_float(gn[j] << 16); f[2 * j + 1] = __uint_as_float(gn[j] & 0xffff0000u); }
;                     if (br < 2) {
;                         const u32x4 gd = *(const u32x4*)(G + row * (3 * DM) + (br + 1) * DM + c);
; #pragma unroll
;                         for (int j = 0; j < 4; ++j) {
;                             f[2 * j] *= __builtin_amdgcn_rcpf(fmaxf(__uint_as_float(gd[j] << 16), 1e-30f));
;                             f[2 * j + 1] *= __builtin_amdgcn_rcpf(fmaxf(__uint_as_float(gd[j] & 0xffff0000u), 1e-30f));
;                         }
; #pragma unroll
;                         for (int i = 0; i < 8; ++i) acc[ai][bj][m][i >> 2][i & 3] *= f[i];
	v_lshlrev_b32_e32 v144, 16, v198
	v_and_b32_e32 v145, 0xffff0000, v198
	v_lshlrev_b32_e32 v146, 16, v199
	v_and_b32_e32 v147, 0xffff0000, v199
	v_lshlrev_b32_e32 v148, 16, v200
	v_and_b32_e32 v149, 0xffff0000, v200
	v_lshlrev_b32_e32 v150, 16, v201
	v_and_b32_e32 v151, 0xffff0000, v201
	v_lshlrev_b32_e32 v152, 16, v194
	v_and_b32_e32 v153, 0xffff0000, v194
	v_lshlrev_b32_e32 v154, 16, v195
	v_and_b32_e32 v155, 0xffff0000, v195
	v_lshlrev_b32_e32 v190, 16, v196
	v_and_b32_e32 v191, 0xffff0000, v196
	v_lshlrev_b32_e32 v2, 16, v197
	v_and_b32_e32 v3, 0xffff0000, v197
	global_load_dwordx4 v[194:197], v183, s[98:99]
	global_load_dwordx4 v[198:201], v183, s[98:99] offset:2048
	v_max_f32_e32 v144, v144, v144
	v_max_f32_e32 v145, v145, v145
	v_max_f32_e32 v146, v146, v146
	v_max_f32_e32 v147, v147, v147
	v_max_f32_e32 v148, v148, v148
	v_max_f32_e32 v149, v149, v149
	v_max_f32_e32 v150, v150, v150
	v_max_f32_e32 v151, v151, v151
	v_max_f32_e32 v144, 0xda24260, v144
	v_max_f32_e32 v145, 0xda24260, v145
	v_max_f32_e32 v146, 0xda24260, v146
	v_max_f32_e32 v147, 0xda24260, v147
	v_max_f32_e32 v148, 0xda24260, v148
	v_max_f32_e32 v149, 0xda24260, v149
	v_max_f32_e32 v150, 0xda24260, v150
	v_max_f32_e32 v151, 0xda24260, v151
	v_rcp_f32_e32 v144, v144
	v_rcp_f32_e32 v145, v145
	v_rcp_f32_e32 v146, v146
	v_rcp_f32_e32 v147, v147
	v_rcp_f32_e32 v148, v148
	v_rcp_f32_e32 v149, v149
	v_rcp_f32_e32 v150, v150
	v_rcp_f32_e32 v151, v151
	s_nop 0
	v_pk_mul_f32 v[152:153], v[144:145], v[152:153]
	v_pk_mul_f32 v[154:155], v[146:147], v[154:155]
	v_pk_mul_f32 v[190:191], v[148:149], v[190:191]
	v_pk_mul_f32 v[2:3], v[150:151], v[2:3]
	v_pk_mul_f32 v[80:81], v[80:81], v[152:153]
	v_pk_mul_f32 v[82:83], v[82:83], v[154:155]
	v_pk_mul_f32 v[76:77], v[76:77], v[190:191]
	v_pk_mul_f32 v[78:79], v[78:79], v[2:3]
	s_waitcnt vmcnt(8)
	v_lshlrev_b32_e32 v144, 16, v206
	v_and_b32_e32 v145, 0xffff0000, v206
	v_lshlrev_b32_e32 v146, 16, v207
	v_and_b32_e32 v147, 0xffff0000, v207
	v_lshlrev_b32_e32 v148, 16, v208
	v_and_b32_e32 v149, 0xffff0000, v208
	v_lshlrev_b32_e32 v150, 16, v209
	v_and_b32_e32 v151, 0xffff0000, v209
	v_lshlrev_b32_e32 v152, 16, v202
	v_and_b32_e32 v153, 0xffff0000, v202
	v_lshlrev_b32_e32 v154, 16, v203
	v_and_b32_e32 v155, 0xffff0000, v203
	v_lshlrev_b32_e32 v190, 16, v204
	v_and_b32_e32 v191, 0xffff0000, v204
	v_lshlrev_b32_e32 v2, 16, v205
	v_and_b32_e32 v3, 0xffff0000, v205
	global_load_dwordx4 v[202:205], v183, s[98:99] offset:256
	global_load_dwordx4 v[206:209], v183, s[98:99] offset:2304
	v_max_f32_e32 v144, v144, v144
	v_max_f32_e32 v145, v145, v145
	v_max_f32_e32 v146, v146, v146
	v_max_f32_e32 v147, v147, v147
	v_max_f32_e32 v148, v148, v148
	v_max_f32_e32 v149, v149, v149
	v_max_f32_e32 v150, v150, v150
	v_max_f32_e32 v151, v151, v151
	v_max_f32_e32 v144, 0xda24260, v144
	v_max_f32_e32 v145, 0xda24260, v145
	v_max_f32_e32 v146, 0xda24260, v146
	v_max_f32_e32 v147, 0xda24260, v147
	v_max_f32_e32 v148, 0xda24260, v148
	v_max_f32_e32 v149, 0xda24260, v149
	v_max_f32_e32 v150, 0xda24260, v150
	v_max_f32_e32 v151, 0xda24260, v151
	v_rcp_f32_e32 v144, v144
	v_rcp_f32_e32 v145, v145
	v_rcp_f32_e32 v146, v146
	v_rcp_f32_e32 v147, v147
	v_rcp_f32_e32 v148, v148
	v_rcp_f32_e32 v149, v149
	v_rcp_f32_e32 v150, v150
	v_rcp_f32_e32 v151, v151
	s_nop 0
	v_pk_mul_f32 v[152:153], v[144:145], v[152:153]
	v_pk_mul_f32 v[154:155], v[146:147], v[154:155]
	v_pk_mul_f32 v[190:191], v[148:149], v[190:191]
	v_pk_mul_f32 v[2:3], v[150:151], v[2:3]
	v_pk_mul_f32 v[104:105], v[104:105], v[152:153]
	v_pk_mul_f32 v[106:107], v[106:107], v[154:155]
	v_pk_mul_f32 v[100:101], v[100:101], v[190:191]
	v_pk_mul_f32 v[102:103], v[102:103], v[2:3]
	s_waitcnt vmcnt(8)
	v_lshlrev_b32_e32 v144, 16, v226
	v_and_b32_e32 v145, 0xffff0000, v226
	v_lshlrev_b32_e32 v146, 16, v227
	v_and_b32_e32 v147, 0xffff0000, v227
	v_lshlrev_b32_e32 v148, 16, v228
	v_and_b32_e32 v149, 0xffff0000, v228
	v_lshlrev_b32_e32 v150, 16, v229
	v_and_b32_e32 v151, 0xffff0000, v229
	v_lshlrev_b32_e32 v152, 16, v210
	v_and_b32_e32 v153, 0xffff0000, v210
	v_lshlrev_b32_e32 v154, 16, v211
	v_and_b32_e32 v155, 0xffff0000, v211
	v_lshlrev_b32_e32 v190, 16, v212
	v_and_b32_e32 v191, 0xffff0000, v212
	v_lshlrev_b32_e32 v2, 16, v213
	v_and_b32_e32 v3, 0xffff0000, v213
	global_load_dwordx4 v[210:213], v184, s[98:99]
	global_load_dwordx4 v[226:229], v184, s[98:99] offset:2048
	v_max_f32_e32 v144, v144, v144
	v_max_f32_e32 v145, v145, v145
	v_max_f32_e32 v146, v146, v146
	v_max_f32_e32 v147, v147, v147
	v_max_f32_e32 v148, v148, v148
	v_max_f32_e32 v149, v149, v149
	v_max_f32_e32 v150, v150, v150
	v_max_f32_e32 v151, v151, v151
	v_max_f32_e32 v144, 0xda24260, v144
	v_max_f32_e32 v145, 0xda24260, v145
	v_max_f32_e32 v146, 0xda24260, v146
	v_max_f32_e32 v147, 0xda24260, v147
	v_max_f32_e32 v148, 0xda24260, v148
	v_max_f32_e32 v149, 0xda24260, v149
	v_max_f32_e32 v150, 0xda24260, v150
	v_max_f32_e32 v151, 0xda24260, v151
	v_rcp_f32_e32 v144, v144
	v_rcp_f32_e32 v145, v145
	v_rcp_f32_e32 v146, v146
	v_rcp_f32_e32 v147, v147
	v_rcp_f32_e32 v148, v148
	v_rcp_f32_e32 v149, v149
	v_rcp_f32_e32 v150, v150
	v_rcp_f32_e32 v151, v151
	s_nop 0
	v_pk_mul_f32 v[152:153], v[144:145], v[152:153]
	v_pk_mul_f32 v[154:155], v[146:147], v[154:155]
	v_pk_mul_f32 v[190:191], v[148:149], v[190:191]
	v_pk_mul_f32 v[2:3], v[150:151], v[2:3]
	v_pk_mul_f32 v[72:73], v[72:73], v[152:153]
	v_pk_mul_f32 v[74:75], v[74:75], v[154:155]
	v_pk_mul_f32 v[68:69], v[68:69], v[190:191]
	v_pk_mul_f32 v[70:71], v[70:71], v[2:3]
	s_waitcnt vmcnt(8)
;     __device__ __forceinline__ bool carry(f32x4 (&acc)[2][2][4][2], const Unit& u, int wr, int wc, int fr, int fq) const {
;     ...
;                     const size_t row = (size_t)(row0 + ai * 128 + m * 16); const int c = col0 + bj * 128;
;                     const u32x4 gn = *(const u32x4*)(G + row * (3 * DM) + br * DM + c);
;                     float f[8];
; #pragma unroll
;                     for (int j = 0; j < 4; ++j) { f[2 * j] = __uint_as_float(gn[j] << 16); f[2 * j + 1] = __uint_as_float(gn[j] & 0xffff0000u); }
;                     if (br < 2) {
;                         const u32x4 gd = *(const u32x4*)(G + row * (3 * DM) + (br + 1) * DM + c);
; #pragma unroll
;                         for (int j = 0; j < 4; ++j) {
;                             f[2 * j] *= __builtin_amdgcn_rcpf(fmaxf(__uint_as_float(gd[j] << 16), 1e-30f));
;                             f[2 * j + 1] *= __builtin_amdgcn_rcpf(fmaxf(__uint_as_float(gd[j] & 0xffff0000u), 1e-30f));
;                         }
; #pragma unroll
;                         for (int i = 0; i < 8; ++i) acc[ai][bj][m][i >> 2][i & 3] *= f[i];
	v_lshlrev_b32_e32 v144, 16, v234
	v_and_b32_e32 v145, 0xffff0000, v234
	v_lshlrev_b32_e32 v146, 16, v235
	v_and_b32_e32 v147, 0xffff0000, v235
	v_lshlrev_b32_e32 v148, 16, v236
	v_and_b32_e32 v149, 0xffff0000, v236
	v_lshlrev_b32_e32 v150, 16, v237
	v_and_b32_e32 v151, 0xffff0000, v237
	v_lshlrev_b32_e32 v152, 16, v230
	v_and_b32_e32 v153, 0xffff0000, v230
	v_lshlrev_b32_e32 v154, 16, v231
	v_and_b32_e32 v155, 0xffff0000, v231
	v_lshlrev_b32_e32 v190, 16, v232
	v_and_b32_e32 v191, 0xffff0000, v232
	v_lshlrev_b32_e32 v2, 16, v233
	v_and_b32_e32 v3, 0xffff0000, v233
	global_load_dwordx4 v[230:233], v184, s[98:99] offset:256
	global_load_dwordx4 v[234:237], v184, s[98:99] offset:2304
	v_max_f32_e32 v144, v144, v144
	v_max_f32_e32 v145, v145, v145
	v_max_f32_e32 v146, v146, v146
	v_max_f32_e32 v147, v147, v147
	v_max_f32_e32 v148, v148, v148
	v_max_f32_e32 v149, v149, v149
	v_max_f32_e32 v150, v150, v150
	v_max_f32_e32 v151, v151, v151
	v_max_f32_e32 v144, 0xda24260, v144
	v_max_f32_e32 v145, 0xda24260, v145
	v_max_f32_e32 v146, 0xda24260, v146
	v_max_f32_e32 v147, 0xda24260, v147
	v_max_f32_e32 v148, 0xda24260, v148
	v_max_f32_e32 v149, 0xda24260, v149
	v_max_f32_e32 v150, 0xda24260, v150
	v_max_f32_e32 v151, 0xda24260, v151
	v_rcp_f32_e32 v144, v144
	v_rcp_f32_e32 v145, v145
	v_rcp_f32_e32 v146, v146
	v_rcp_f32_e32 v147, v147
	v_rcp_f32_e32 v148, v148
	v_rcp_f32_e32 v149, v149
	v_rcp_f32_e32 v150, v150
	v_rcp_f32_e32 v151, v151
	s_nop 0
	v_pk_mul_f32 v[152:153], v[144:145], v[152:153]
	v_pk_mul_f32 v[154:155], v[146:147], v[154:155]
	v_pk_mul_f32 v[190:191], v[148:149], v[190:191]
	v_pk_mul_f32 v[2:3], v[150:151], v[2:3]
	v_pk_mul_f32 v[64:65], v[64:65], v[152:153]
	v_pk_mul_f32 v[66:67], v[66:67], v[154:155]
	v_pk_mul_f32 v[60:61], v[60:61], v[190:191]
	v_pk_mul_f32 v[62:63], v[62:63], v[2:3]
	s_waitcnt vmcnt(8)
	v_lshlrev_b32_e32 v144, 16, v242
	v_and_b32_e32 v145, 0xffff0000, v242
	v_lshlrev_b32_e32 v146, 16, v243
	v_and_b32_e32 v147, 0xffff0000, v243
	v_lshlrev_b32_e32 v148, 16, v244
	v_and_b32_e32 v149, 0xffff0000, v244
	v_lshlrev_b32_e32 v150, 16, v245
	v_and_b32_e32 v151, 0xffff0000, v245
	v_lshlrev_b32_e32 v152, 16, v238
	v_and_b32_e32 v153, 0xffff0000, v238
	v_lshlrev_b32_e32 v154, 16, v239
	v_and_b32_e32 v155, 0xffff0000, v239
	v_lshlrev_b32_e32 v190, 16, v240
	v_and_b32_e32 v191, 0xffff0000, v240
	v_lshlrev_b32_e32 v2, 16, v241
	v_and_b32_e32 v3, 0xffff0000, v241
	global_load_dwordx4 v[238:241], v185, s[98:99]
	global_load_dwordx4 v[242:245], v185, s[98:99] offset:2048
	v_max_f32_e32 v144, v144, v144
	v_max_f32_e32 v145, v145, v145
	v_max_f32_e32 v146, v146, v146
	v_max_f32_e32 v147, v147, v147
	v_max_f32_e32 v148, v148, v148
	v_max_f32_e32 v149, v149, v149
	v_max_f32_e32 v150, v150, v150
	v_max_f32_e32 v151, v151, v151
	v_max_f32_e32 v144, 0xda24260, v144
	v_max_f32_e32 v145, 0xda24260, v145
	v_max_f32_e32 v146, 0xda24260, v146
	v_max_f32_e32 v147, 0xda24260, v147
	v_max_f32_e32 v148, 0xda24260, v148
	v_max_f32_e32 v149, 0xda24260, v149
	v_max_f32_e32 v150, 0xda24260, v150
	v_max_f32_e32 v151, 0xda24260, v151
	v_rcp_f32_e32 v144, v144
	v_rcp_f32_e32 v145, v145
	v_rcp_f32_e32 v146, v146
	v_rcp_f32_e32 v147, v147
	v_rcp_f32_e32 v148, v148
	v_rcp_f32_e32 v149, v149
	v_rcp_f32_e32 v150, v150
	v_rcp_f32_e32 v151, v151
	s_nop 0
	v_pk_mul_f32 v[152:153], v[144:145], v[152:153]
	v_pk_mul_f32 v[154:155], v[146:147], v[154:155]
	v_pk_mul_f32 v[190:191], v[148:149], v[190:191]
	v_pk_mul_f32 v[2:3], v[150:151], v[2:3]
	v_pk_mul_f32 v[32:33], v[32:33], v[152:153]
	v_pk_mul_f32 v[34:35], v[34:35], v[154:155]
	v_pk_mul_f32 v[28:29], v[28:29], v[190:191]
	v_pk_mul_f32 v[30:31], v[30:31], v[2:3]
	s_waitcnt vmcnt(8)
	v_lshlrev_b32_e32 v144, 16, v198
	v_and_b32_e32 v145, 0xffff0000, v198
	v_lshlrev_b32_e32 v146, 16, v199
	v_and_b32_e32 v147, 0xffff0000, v199
	v_lshlrev_b32_e32 v148, 16, v200
	v_and_b32_e32 v149, 0xffff0000, v200
	v_lshlrev_b32_e32 v150, 16, v201
	v_and_b32_e32 v151, 0xffff0000, v201
	v_lshlrev_b32_e32 v152, 16, v194
	v_and_b32_e32 v153, 0xffff0000, v194
	v_lshlrev_b32_e32 v154, 16, v195
	v_and_b32_e32 v155, 0xffff0000, v195
	v_lshlrev_b32_e32 v190, 16, v196
	v_and_b32_e32 v191, 0xffff0000, v196
	v_lshlrev_b32_e32 v2, 16, v197
	v_and_b32_e32 v3, 0xffff0000, v197
	global_load_dwordx4 v[194:197], v185, s[98:99] offset:256
	global_load_dwordx4 v[198:201], v185, s[98:99] offset:2304
	v_max_f32_e32 v144, v144, v144
	v_max_f32_e32 v145, v145, v145
	v_max_f32_e32 v146, v146, v146
	v_max_f32_e32 v147, v147, v147
	v_max_f32_e32 v148, v148, v148
	v_max_f32_e32 v149, v149, v149
	v_max_f32_e32 v150, v150, v150
	v_max_f32_e32 v151, v151, v151
	v_max_f32_e32 v144, 0xda24260, v144
	v_max_f32_e32 v145, 0xda24260, v145
	v_max_f32_e32 v146, 0xda24260, v146
	v_max_f32_e32 v147, 0xda24260, v147
	v_max_f32_e32 v148, 0xda24260, v148
	v_max_f32_e32 v149, 0xda24260, v149
	v_max_f32_e32 v150, 0xda24260, v150
	v_max_f32_e32 v151, 0xda24260, v151
	v_rcp_f32_e32 v144, v144
	v_rcp_f32_e32 v145, v145
	v_rcp_f32_e32 v146, v146
	v_rcp_f32_e32 v147, v147
	v_rcp_f32_e32 v148, v148
	v_rcp_f32_e32 v149, v149
	v_rcp_f32_e32 v150, v150
	v_rcp_f32_e32 v151, v151
	s_nop 0
	v_pk_mul_f32 v[152:153], v[144:145], v[152:153]
	v_pk_mul_f32 v[154:155], v[146:147], v[154:155]
	v_pk_mul_f32 v[190:191], v[148:149], v[190:191]
	v_pk_mul_f32 v[2:3], v[150:151], v[2:3]
	v_pk_mul_f32 v[56:57], v[56:57], v[152:153]
	v_pk_mul_f32 v[58:59], v[58:59], v[154:155]
	v_pk_mul_f32 v[52:53], v[52:53], v[190:191]
	v_pk_mul_f32 v[54:55], v[54:55], v[2:3]
	s_waitcnt vmcnt(8)
;     __device__ __forceinline__ bool carry(f32x4 (&acc)[2][2][4][2], const Unit& u, int wr, int wc, int fr, int fq) const {
;     ...
;                     const size_t row = (size_t)(row0 + ai * 128 + m * 16); const int c = col0 + bj * 128;
;                     const u32x4 gn = *(const u32x4*)(G + row * (3 * DM) + br * DM + c);
;                     float f[8];
; #pragma unroll
;                     for (int j = 0; j < 4; ++j) { f[2 * j] = __uint_as_float(gn[j] << 16); f[2 * j + 1] = __uint_as_float(gn[j] & 0xffff0000u); }
;                     if (br < 2) {
;                         const u32x4 gd = *(const u32x4*)(G + row * (3 * DM) + (br + 1) * DM + c);
; #pragma unroll
;                         for (int j = 0; j < 4; ++j) {
;                             f[2 * j] *= __builtin_amdgcn_rcpf(fmaxf(__uint_as_float(gd[j] << 16), 1e-30f));
;                             f[2 * j + 1] *= __builtin_amdgcn_rcpf(fmaxf(__uint_as_float(gd[j] & 0xffff0000u), 1e-30f));
;                         }
; #pragma unroll
;                         for (int i = 0; i < 8; ++i) acc[ai][bj][m][i >> 2][i & 3] *= f[i];
	v_lshlrev_b32_e32 v144, 16, v206
	v_and_b32_e32 v145, 0xffff0000, v206
	v_lshlrev_b32_e32 v146, 16, v207
	v_and_b32_e32 v147, 0xffff0000, v207
	v_lshlrev_b32_e32 v148, 16, v208
	v_and_b32_e32 v149, 0xffff0000, v208
	v_lshlrev_b32_e32 v150, 16, v209
	v_and_b32_e32 v151, 0xffff0000, v209
	v_lshlrev_b32_e32 v152, 16, v202
	v_and_b32_e32 v153, 0xffff0000, v202
	v_lshlrev_b32_e32 v154, 16, v203
	v_and_b32_e32 v155, 0xffff0000, v203
	v_lshlrev_b32_e32 v190, 16, v204
	v_and_b32_e32 v191, 0xffff0000, v204
	v_lshlrev_b32_e32 v2, 16, v205
	v_and_b32_e32 v3, 0xffff0000, v205
	v_max_f32_e32 v144, v144, v144
	v_max_f32_e32 v145, v145, v145
	v_max_f32_e32 v146, v146, v146
	v_max_f32_e32 v147, v147, v147
	v_max_f32_e32 v148, v148, v148
	v_max_f32_e32 v149, v149, v149
	v_max_f32_e32 v150, v150, v150
	v_max_f32_e32 v151, v151, v151
	v_max_f32_e32 v144, 0xda24260, v144
	v_max_f32_e32 v145, 0xda24260, v145
	v_max_f32_e32 v146, 0xda24260, v146
	v_max_f32_e32 v147, 0xda24260, v147
	v_max_f32_e32 v148, 0xda24260, v148
	v_max_f32_e32 v149, 0xda24260, v149
	v_max_f32_e32 v150, 0xda24260, v150
	v_max_f32_e32 v151, 0xda24260, v151
	v_rcp_f32_e32 v144, v144
	v_rcp_f32_e32 v145, v145
	v_rcp_f32_e32 v146, v146
	v_rcp_f32_e32 v147, v147
	v_rcp_f32_e32 v148, v148
	v_rcp_f32_e32 v149, v149
	v_rcp_f32_e32 v150, v150
	v_rcp_f32_e32 v151, v151
	s_nop 0
	v_pk_mul_f32 v[152:153], v[144:145], v[152:153]
	v_pk_mul_f32 v[154:155], v[146:147], v[154:155]
	v_pk_mul_f32 v[190:191], v[148:149], v[190:191]
	v_pk_mul_f32 v[2:3], v[150:151], v[2:3]
	v_pk_mul_f32 v[24:25], v[24:25], v[152:153]
	v_pk_mul_f32 v[26:27], v[26:27], v[154:155]
	v_pk_mul_f32 v[20:21], v[20:21], v[190:191]
	v_pk_mul_f32 v[22:23], v[22:23], v[2:3]
	s_waitcnt vmcnt(6)
	v_lshlrev_b32_e32 v144, 16, v226
	v_and_b32_e32 v145, 0xffff0000, v226
	v_lshlrev_b32_e32 v146, 16, v227
	v_and_b32_e32 v147, 0xffff0000, v227
	v_lshlrev_b32_e32 v148, 16, v228
	v_and_b32_e32 v149, 0xffff0000, v228
	v_lshlrev_b32_e32 v150, 16, v229
	v_and_b32_e32 v151, 0xffff0000, v229
	v_lshlrev_b32_e32 v152, 16, v210
	v_and_b32_e32 v153, 0xffff0000, v210
	v_lshlrev_b32_e32 v154, 16, v211
	v_and_b32_e32 v155, 0xffff0000, v211
	v_lshlrev_b32_e32 v190, 16, v212
	v_and_b32_e32 v191, 0xffff0000, v212
	v_lshlrev_b32_e32 v2, 16, v213
	v_and_b32_e32 v3, 0xffff0000, v213
	v_max_f32_e32 v144, v144, v144
	v_max_f32_e32 v145, v145, v145
	v_max_f32_e32 v146, v146, v146
	v_max_f32_e32 v147, v147, v147
	v_max_f32_e32 v148, v148, v148
	v_max_f32_e32 v149, v149, v149
	v_max_f32_e32 v150, v150, v150
	v_max_f32_e32 v151, v151, v151
	v_max_f32_e32 v144, 0xda24260, v144
	v_max_f32_e32 v145, 0xda24260, v145
	v_max_f32_e32 v146, 0xda24260, v146
	v_max_f32_e32 v147, 0xda24260, v147
	v_max_f32_e32 v148, 0xda24260, v148
	v_max_f32_e32 v149, 0xda24260, v149
	v_max_f32_e32 v150, 0xda24260, v150
	v_max_f32_e32 v151, 0xda24260, v151
	v_rcp_f32_e32 v144, v144
	v_rcp_f32_e32 v145, v145
	v_rcp_f32_e32 v146, v146
	v_rcp_f32_e32 v147, v147
	v_rcp_f32_e32 v148, v148
	v_rcp_f32_e32 v149, v149
	v_rcp_f32_e32 v150, v150
	v_rcp_f32_e32 v151, v151
	s_nop 0
	v_pk_mul_f32 v[152:153], v[144:145], v[152:153]
	v_pk_mul_f32 v[154:155], v[146:147], v[154:155]
	v_pk_mul_f32 v[190:191], v[148:149], v[190:191]
	v_pk_mul_f32 v[2:3], v[150:151], v[2:3]
	v_pk_mul_f32 v[48:49], v[48:49], v[152:153]
	v_pk_mul_f32 v[50:51], v[50:51], v[154:155]
	v_pk_mul_f32 v[44:45], v[44:45], v[190:191]
	v_pk_mul_f32 v[46:47], v[46:47], v[2:3]
	s_waitcnt vmcnt(4)
	v_lshlrev_b32_e32 v144, 16, v234
	v_and_b32_e32 v145, 0xffff0000, v234
	v_lshlrev_b32_e32 v146, 16, v235
	v_and_b32_e32 v147, 0xffff0000, v235
	v_lshlrev_b32_e32 v148, 16, v236
	v_and_b32_e32 v149, 0xffff0000, v236
	v_lshlrev_b32_e32 v150, 16, v237
	v_and_b32_e32 v151, 0xffff0000, v237
	v_lshlrev_b32_e32 v152, 16, v230
	v_and_b32_e32 v153, 0xffff0000, v230
	v_lshlrev_b32_e32 v154, 16, v231
	v_and_b32_e32 v155, 0xffff0000, v231
	v_lshlrev_b32_e32 v190, 16, v232
	v_and_b32_e32 v191, 0xffff0000, v232
	v_lshlrev_b32_e32 v2, 16, v233
	v_and_b32_e32 v3, 0xffff0000, v233
	v_max_f32_e32 v144, v144, v144
	v_max_f32_e32 v145, v145, v145
	v_max_f32_e32 v146, v146, v146
	v_max_f32_e32 v147, v147, v147
	v_max_f32_e32 v148, v148, v148
	v_max_f32_e32 v149, v149, v149
	v_max_f32_e32 v150, v150, v150
	v_max_f32_e32 v151, v151, v151
	v_max_f32_e32 v144, 0xda24260, v144
	v_max_f32_e32 v145, 0xda24260, v145
	v_max_f32_e32 v146, 0xda24260, v146
	v_max_f32_e32 v147, 0xda24260, v147
	v_max_f32_e32 v148, 0xda24260, v148
	v_max_f32_e32 v149, 0xda24260, v149
	v_max_f32_e32 v150, 0xda24260, v150
	v_max_f32_e32 v151, 0xda24260, v151
	v_rcp_f32_e32 v144, v144
	v_rcp_f32_e32 v145, v145
	v_rcp_f32_e32 v146, v146
	v_rcp_f32_e32 v147, v147
	v_rcp_f32_e32 v148, v148
	v_rcp_f32_e32 v149, v149
	v_rcp_f32_e32 v150, v150
	v_rcp_f32_e32 v151, v151
	s_nop 0
	v_pk_mul_f32 v[152:153], v[144:145], v[152:153]
	v_pk_mul_f32 v[154:155], v[146:147], v[154:155]
	v_pk_mul_f32 v[190:191], v[148:149], v[190:191]
	v_pk_mul_f32 v[2:3], v[150:151], v[2:3]
	v_pk_mul_f32 v[16:17], v[16:17], v[152:153]
	v_pk_mul_f32 v[18:19], v[18:19], v[154:155]
	v_pk_mul_f32 v[12:13], v[12:13], v[190:191]
	v_pk_mul_f32 v[14:15], v[14:15], v[2:3]
	s_waitcnt vmcnt(2)
; __device__ __forceinline__ unsigned cvt_pk(float lo, float hi) { f32x2_t v = {lo, hi}; bf16x2_t b = __builtin_convertvector(v, bf16x2_t); return __builtin_bit_cast(unsigned, b); }
;     __device__ __forceinline__ bool carry(f32x4 (&acc)[2][2][4][2], const Unit& u, int wr, int wc, int fr, int fq) const {
;     ...
;                     const size_t row = (size_t)(row0 + ai * 128 + m * 16); const int c = col0 + bj * 128;
;                     const u32x4 gn = *(const u32x4*)(G + row * (3 * DM) + br * DM + c);
;                     float f[8];
; #pragma unroll
;                     for (int j = 0; j < 4; ++j) { f[2 * j] = __uint_as_float(gn[j] << 16); f[2 * j + 1] = __uint_as_float(gn[j] & 0xffff0000u); }
;                     if (br < 2) {
;                         const u32x4 gd = *(const u32x4*)(G + row * (3 * DM) + (br + 1) * DM + c);
; #pragma unroll
;                         for (int j = 0; j < 4; ++j) {
;                             f[2 * j] *= __builtin_amdgcn_rcpf(fmaxf(__uint_as_float(gd[j] << 16), 1e-30f));
;                             f[2 * j + 1] *= __builtin_amdgcn_rcpf(fmaxf(__uint_as_float(gd[j] & 0xffff0000u), 1e-30f));
;                         }
; #pragma unroll
;                         for (int i = 0; i < 8; ++i) acc[ai][bj][m][i >> 2][i & 3] *= f[i];
;                     } else {
;                         float v[8];
; #pragma unroll
;                         for (int i = 0; i < 8; ++i) v[i] = acc[ai][bj][m][i >> 2][i & 3] * f[i];
;                         u32x4 w; w.x = cvt_pk(v[0], v[1]); w.y = cvt_pk(v[2], v[3]); w.z = cvt_pk(v[4], v[5]); w.w = cvt_pk(v[6], v[7]);
;                         *(u32x4*)(Mg + row * DM + c) = w;
;                     }
	v_lshlrev_b32_e32 v144, 16, v242
	v_and_b32_e32 v145, 0xffff0000, v242
	v_lshlrev_b32_e32 v146, 16, v243
	v_and_b32_e32 v147, 0xffff0000, v243
	v_lshlrev_b32_e32 v148, 16, v244
	v_and_b32_e32 v149, 0xffff0000, v244
	v_lshlrev_b32_e32 v150, 16, v245
	v_and_b32_e32 v151, 0xffff0000, v245
	v_lshlrev_b32_e32 v152, 16, v238
	v_and_b32_e32 v153, 0xffff0000, v238
	v_lshlrev_b32_e32 v154, 16, v239
	v_and_b32_e32 v155, 0xffff0000, v239
	v_lshlrev_b32_e32 v190, 16, v240
	v_and_b32_e32 v191, 0xffff0000, v240
	v_lshlrev_b32_e32 v2, 16, v241
	v_and_b32_e32 v3, 0xffff0000, v241
	v_max_f32_e32 v144, v144, v144
	v_max_f32_e32 v145, v145, v145
	v_max_f32_e32 v146, v146, v146
	v_max_f32_e32 v147, v147, v147
	v_max_f32_e32 v148, v148, v148
	v_max_f32_e32 v149, v149, v149
	v_max_f32_e32 v150, v150, v150
	v_max_f32_e32 v151, v151, v151
	v_max_f32_e32 v144, 0xda24260, v144
	v_max_f32_e32 v145, 0xda24260, v145
	v_max_f32_e32 v146, 0xda24260, v146
	v_max_f32_e32 v147, 0xda24260, v147
	v_max_f32_e32 v148, 0xda24260, v148
	v_max_f32_e32 v149, 0xda24260, v149
	v_max_f32_e32 v150, 0xda24260, v150
	v_max_f32_e32 v151, 0xda24260, v151
	v_rcp_f32_e32 v144, v144
	v_rcp_f32_e32 v145, v145
	v_rcp_f32_e32 v146, v146
	v_rcp_f32_e32 v147, v147
	v_rcp_f32_e32 v148, v148
	v_rcp_f32_e32 v149, v149
	v_rcp_f32_e32 v150, v150
	v_rcp_f32_e32 v151, v151
	s_nop 0
	v_pk_mul_f32 v[152:153], v[144:145], v[152:153]
	v_pk_mul_f32 v[154:155], v[146:147], v[154:155]
	v_pk_mul_f32 v[190:191], v[148:149], v[190:191]
	v_pk_mul_f32 v[2:3], v[150:151], v[2:3]
	v_pk_mul_f32 v[40:41], v[40:41], v[152:153]
	v_pk_mul_f32 v[42:43], v[42:43], v[154:155]
	v_pk_mul_f32 v[36:37], v[36:37], v[190:191]
	v_pk_mul_f32 v[38:39], v[38:39], v[2:3]
	s_waitcnt vmcnt(0)
	v_lshlrev_b32_e32 v144, 16, v198
	v_and_b32_e32 v145, 0xffff0000, v198
	v_lshlrev_b32_e32 v146, 16, v199
	v_and_b32_e32 v147, 0xffff0000, v199
	v_lshlrev_b32_e32 v148, 16, v200
	v_and_b32_e32 v149, 0xffff0000, v200
	v_lshlrev_b32_e32 v150, 16, v201
	v_and_b32_e32 v151, 0xffff0000, v201
	v_lshlrev_b32_e32 v152, 16, v194
	v_and_b32_e32 v153, 0xffff0000, v194
	v_lshlrev_b32_e32 v154, 16, v195
	v_and_b32_e32 v155, 0xffff0000, v195
	v_lshlrev_b32_e32 v190, 16, v196
	v_and_b32_e32 v191, 0xffff0000, v196
	v_lshlrev_b32_e32 v2, 16, v197
	v_and_b32_e32 v3, 0xffff0000, v197
	v_max_f32_e32 v144, v144, v144
	v_max_f32_e32 v145, v145, v145
	v_max_f32_e32 v146, v146, v146
	v_max_f32_e32 v147, v147, v147
	v_max_f32_e32 v148, v148, v148
	v_max_f32_e32 v149, v149, v149
	v_max_f32_e32 v150, v150, v150
	v_max_f32_e32 v151, v151, v151
	v_max_f32_e32 v144, 0xda24260, v144
	v_max_f32_e32 v145, 0xda24260, v145
	v_max_f32_e32 v146, 0xda24260, v146
	v_max_f32_e32 v147, 0xda24260, v147
	v_max_f32_e32 v148, 0xda24260, v148
	v_max_f32_e32 v149, 0xda24260, v149
	v_max_f32_e32 v150, 0xda24260, v150
	v_max_f32_e32 v151, 0xda24260, v151
	v_rcp_f32_e32 v144, v144
	v_rcp_f32_e32 v145, v145
	v_rcp_f32_e32 v146, v146
	v_rcp_f32_e32 v147, v147
	v_rcp_f32_e32 v148, v148
	v_rcp_f32_e32 v149, v149
	v_rcp_f32_e32 v150, v150
	v_rcp_f32_e32 v151, v151
	s_nop 0
	v_pk_mul_f32 v[152:153], v[144:145], v[152:153]
	v_pk_mul_f32 v[154:155], v[146:147], v[154:155]
	v_pk_mul_f32 v[190:191], v[148:149], v[190:191]
	v_pk_mul_f32 v[2:3], v[150:151], v[2:3]
	v_pk_mul_f32 v[8:9], v[8:9], v[152:153]
	v_pk_mul_f32 v[10:11], v[10:11], v[154:155]
	v_pk_mul_f32 v[4:5], v[4:5], v[190:191]
	v_pk_mul_f32 v[6:7], v[6:7], v[2:3]
	s_branch .Lmg_done
.Lmg_final:
	global_load_dwordx4 v[194:197], v182, s[24:25]
	global_load_dwordx4 v[202:205], v182, s[24:25] offset:256
	global_load_dwordx4 v[210:213], v183, s[24:25]
	global_load_dwordx4 v[230:233], v183, s[24:25] offset:256
	global_load_dwordx4 v[238:241], v184, s[24:25]
	s_waitcnt vmcnt(4)
	v_lshlrev_b32_e32 v152, 16, v194
	v_and_b32_e32 v153, 0xffff0000, v194
	v_lshlrev_b32_e32 v154, 16, v195
	v_and_b32_e32 v155, 0xffff0000, v195
	v_lshlrev_b32_e32 v190, 16, v196
	v_and_b32_e32 v191, 0xffff0000, v196
	v_lshlrev_b32_e32 v2, 16, v197
	v_and_b32_e32 v3, 0xffff0000, v197
	global_load_dwordx4 v[194:197], v184, s[24:25] offset:256
	v_pk_mul_f32 v[152:153], v[128:129], v[152:153]
	v_pk_mul_f32 v[154:155], v[130:131], v[154:155]
	v_pk_mul_f32 v[190:191], v[124:125], v[190:191]
	v_pk_mul_f32 v[2:3], v[126:127], v[2:3]
	v_cvt_pk_bf16_f32 v144, v152, v153
	v_cvt_pk_bf16_f32 v145, v154, v155
	v_cvt_pk_bf16_f32 v146, v190, v191
	v_cvt_pk_bf16_f32 v147, v2, v3
	global_store_dwordx4 v186, v[144:147], s[72:73]
	s_nop 1
	s_waitcnt vmcnt(5)
	v_lshlrev_b32_e32 v152, 16, v202
	v_and_b32_e32 v153, 0xffff0000, v202
	v_lshlrev_b32_e32 v154, 16, v203
	v_and_b32_e32 v155, 0xffff0000, v203
	v_lshlrev_b32_e32 v190, 16, v204
	v_and_b32_e32 v191, 0xffff0000, v204
	v_lshlrev_b32_e32 v2, 16, v205
	v_and_b32_e32 v3, 0xffff0000, v205
	global_load_dwordx4 v[202:205], v185, s[24:25]
	v_pk_mul_f32 v[152:153], v[96:97], v[152:153]
	v_pk_mul_f32 v[154:155], v[98:99], v[154:155]
	v_pk_mul_f32 v[190:191], v[92:93], v[190:191]
	v_pk_mul_f32 v[2:3], v[94:95], v[2:3]
	v_cvt_pk_bf16_f32 v144, v152, v153
	v_cvt_pk_bf16_f32 v145, v154, v155
	v_cvt_pk_bf16_f32 v146, v190, v191
	v_cvt_pk_bf16_f32 v147, v2, v3
	global_store_dwordx4 v186, v[144:147], s[72:73] offset:256
	s_nop 1
	s_waitcnt vmcnt(6)
	v_lshlrev_b32_e32 v152, 16, v210
	v_and_b32_e32 v153, 0xffff0000, v210
	v_lshlrev_b32_e32 v154, 16, v211
	v_and_b32_e32 v155, 0xffff0000, v211
	v_lshlrev_b32_e32 v190, 16, v212
	v_and_b32_e32 v191, 0xffff0000, v212
	v_lshlrev_b32_e32 v2, 16, v213
	v_and_b32_e32 v3, 0xffff0000, v213
	global_load_dwordx4 v[210:213], v185, s[24:25] offset:256
	v_pk_mul_f32 v[152:153], v[120:121], v[152:153]
	v_pk_mul_f32 v[154:155], v[122:123], v[154:155]
	v_pk_mul_f32 v[190:191], v[116:117], v[190:191]
	v_pk_mul_f32 v[2:3], v[118:119], v[2:3]
	v_cvt_pk_bf16_f32 v144, v152, v153
	v_cvt_pk_bf16_f32 v145, v154, v155
	v_cvt_pk_bf16_f32 v146, v190, v191
	v_cvt_pk_bf16_f32 v147, v2, v3
	global_store_dwordx4 v187, v[144:147], s[72:73]
	s_nop 1
	s_waitcnt vmcnt(7)
; __device__ __forceinline__ unsigned cvt_pk(float lo, float hi) { f32x2_t v = {lo, hi}; bf16x2_t b = __builtin_convertvector(v, bf16x2_t); return __builtin_bit_cast(unsigned, b); }
;     __device__ __forceinline__ bool carry(f32x4 (&acc)[2][2][4][2], const Unit& u, int wr, int wc, int fr, int fq) const {
;     ...
;                     } else {
;                         float v[8];
; #pragma unroll
;                         for (int i = 0; i < 8; ++i) v[i] = acc[ai][bj][m][i >> 2][i & 3] * f[i];
;                         u32x4 w; w.x = cvt_pk(v[0], v[1]); w.y = cvt_pk(v[2], v[3]); w.z = cvt_pk(v[4], v[5]); w.w = cvt_pk(v[6], v[7]);
;                         *(u32x4*)(Mg + row * DM + c) = w;
;                     }
	v_lshlrev_b32_e32 v152, 16, v230
	v_and_b32_e32 v153, 0xffff0000, v230
	v_lshlrev_b32_e32 v154, 16, v231
	v_and_b32_e32 v155, 0xffff0000, v231
	v_lshlrev_b32_e32 v190, 16, v232
	v_and_b32_e32 v191, 0xffff0000, v232
	v_lshlrev_b32_e32 v2, 16, v233
	v_and_b32_e32 v3, 0xffff0000, v233
	global_load_dwordx4 v[230:233], v182, s[98:99]
	v_pk_mul_f32 v[152:153], v[88:89], v[152:153]
	v_pk_mul_f32 v[154:155], v[90:91], v[154:155]
	v_pk_mul_f32 v[190:191], v[84:85], v[190:191]
	v_pk_mul_f32 v[2:3], v[86:87], v[2:3]
	v_cvt_pk_bf16_f32 v144, v152, v153
	v_cvt_pk_bf16_f32 v145, v154, v155
	v_cvt_pk_bf16_f32 v146, v190, v191
	v_cvt_pk_bf16_f32 v147, v2, v3
	global_store_dwordx4 v187, v[144:147], s[72:73] offset:256
	s_nop 1
	s_waitcnt vmcnt(8)
	v_lshlrev_b32_e32 v152, 16, v238
	v_and_b32_e32 v153, 0xffff0000, v238
	v_lshlrev_b32_e32 v154, 16, v239
	v_and_b32_e32 v155, 0xffff0000, v239
	v_lshlrev_b32_e32 v190, 16, v240
	v_and_b32_e32 v191, 0xffff0000, v240
	v_lshlrev_b32_e32 v2, 16, v241
	v_and_b32_e32 v3, 0xffff0000, v241
	global_load_dwordx4 v[238:241], v182, s[98:99] offset:256
	v_pk_mul_f32 v[152:153], v[112:113], v[152:153]
	v_pk_mul_f32 v[154:155], v[114:115], v[154:155]
	v_pk_mul_f32 v[190:191], v[108:109], v[190:191]
	v_pk_mul_f32 v[2:3], v[110:111], v[2:3]
	v_cvt_pk_bf16_f32 v144, v152, v153
	v_cvt_pk_bf16_f32 v145, v154, v155
	v_cvt_pk_bf16_f32 v146, v190, v191
	v_cvt_pk_bf16_f32 v147, v2, v3
	global_store_dwordx4 v188, v[144:147], s[72:73]
	s_nop 1
	s_waitcnt vmcnt(9)
	v_lshlrev_b32_e32 v152, 16, v194
	v_and_b32_e32 v153, 0xffff0000, v194
	v_lshlrev_b32_e32 v154, 16, v195
	v_and_b32_e32 v155, 0xffff0000, v195
	v_lshlrev_b32_e32 v190, 16, v196
	v_and_b32_e32 v191, 0xffff0000, v196
	v_lshlrev_b32_e32 v2, 16, v197
	v_and_b32_e32 v3, 0xffff0000, v197
	global_load_dwordx4 v[194:197], v183, s[98:99]
	v_pk_mul_f32 v[152:153], v[80:81], v[152:153]
	v_pk_mul_f32 v[154:155], v[82:83], v[154:155]
	v_pk_mul_f32 v[190:191], v[76:77], v[190:191]
	v_pk_mul_f32 v[2:3], v[78:79], v[2:3]
	v_cvt_pk_bf16_f32 v144, v152, v153
	v_cvt_pk_bf16_f32 v145, v154, v155
	v_cvt_pk_bf16_f32 v146, v190, v191
	v_cvt_pk_bf16_f32 v147, v2, v3
	global_store_dwordx4 v188, v[144:147], s[72:73] offset:256
	s_nop 1
	s_waitcnt vmcnt(9)
	v_lshlrev_b32_e32 v152, 16, v202
	v_and_b32_e32 v153, 0xffff0000, v202
	v_lshlrev_b32_e32 v154, 16, v203
	v_and_b32_e32 v155, 0xffff0000, v203
	v_lshlrev_b32_e32 v190, 16, v204
	v_and_b32_e32 v191, 0xffff0000, v204
	v_lshlrev_b32_e32 v2, 16, v205
	v_and_b32_e32 v3, 0xffff0000, v205
	global_load_dwordx4 v[202:205], v183, s[98:99] offset:256
	v_pk_mul_f32 v[152:153], v[104:105], v[152:153]
	v_pk_mul_f32 v[154:155], v[106:107], v[154:155]
	v_pk_mul_f32 v[190:191], v[100:101], v[190:191]
	v_pk_mul_f32 v[2:3], v[102:103], v[2:3]
	v_cvt_pk_bf16_f32 v144, v152, v153
	v_cvt_pk_bf16_f32 v145, v154, v155
	v_cvt_pk_bf16_f32 v146, v190, v191
	v_cvt_pk_bf16_f32 v147, v2, v3
	global_store_dwordx4 v189, v[144:147], s[72:73]
	s_nop 1
	s_waitcnt vmcnt(9)
	v_lshlrev_b32_e32 v152, 16, v210
	v_and_b32_e32 v153, 0xffff0000, v210
	v_lshlrev_b32_e32 v154, 16, v211
	v_and_b32_e32 v155, 0xffff0000, v211
	v_lshlrev_b32_e32 v190, 16, v212
	v_and_b32_e32 v191, 0xffff0000, v212
	v_lshlrev_b32_e32 v2, 16, v213
	v_and_b32_e32 v3, 0xffff0000, v213
	global_load_dwordx4 v[210:213], v184, s[98:99]
	v_pk_mul_f32 v[152:153], v[72:73], v[152:153]
	v_pk_mul_f32 v[154:155], v[74:75], v[154:155]
	v_pk_mul_f32 v[190:191], v[68:69], v[190:191]
	v_pk_mul_f32 v[2:3], v[70:71], v[2:3]
	v_cvt_pk_bf16_f32 v144, v152, v153
	v_cvt_pk_bf16_f32 v145, v154, v155
	v_cvt_pk_bf16_f32 v146, v190, v191
	v_cvt_pk_bf16_f32 v147, v2, v3
	global_store_dwordx4 v189, v[144:147], s[72:73] offset:256
	s_nop 1
	s_waitcnt vmcnt(9)
	v_lshlrev_b32_e32 v152, 16, v230
	v_and_b32_e32 v153, 0xffff0000, v230
	v_lshlrev_b32_e32 v154, 16, v231
	v_and_b32_e32 v155, 0xffff0000, v231
	v_lshlrev_b32_e32 v190, 16, v232
	v_and_b32_e32 v191, 0xffff0000, v232
	v_lshlrev_b32_e32 v2, 16, v233
	v_and_b32_e32 v3, 0xffff0000, v233
	global_load_dwordx4 v[230:233], v184, s[98:99] offset:256
	v_pk_mul_f32 v[152:153], v[64:65], v[152:153]
	v_pk_mul_f32 v[154:155], v[66:67], v[154:155]
	v_pk_mul_f32 v[190:191], v[60:61], v[190:191]
	v_pk_mul_f32 v[2:3], v[62:63], v[2:3]
	v_cvt_pk_bf16_f32 v144, v152, v153
	v_cvt_pk_bf16_f32 v145, v154, v155
	v_cvt_pk_bf16_f32 v146, v190, v191
	v_cvt_pk_bf16_f32 v147, v2, v3
	global_store_dwordx4 v186, v[144:147], s[100:101]
	s_nop 1
	s_waitcnt vmcnt(9)
	v_lshlrev_b32_e32 v152, 16, v238
	v_and_b32_e32 v153, 0xffff0000, v238
	v_lshlrev_b32_e32 v154, 16, v239
	v_and_b32_e32 v155, 0xffff0000, v239
	v_lshlrev_b32_e32 v190, 16, v240
	v_and_b32_e32 v191, 0xffff0000, v240
	v_lshlrev_b32_e32 v2, 16, v241
	v_and_b32_e32 v3, 0xffff0000, v241
	global_load_dwordx4 v[238:241], v185, s[98:99]
	v_pk_mul_f32 v[152:153], v[32:33], v[152:153]
	v_pk_mul_f32 v[154:155], v[34:35], v[154:155]
	v_pk_mul_f32 v[190:191], v[28:29], v[190:191]
	v_pk_mul_f32 v[2:3], v[30:31], v[2:3]
	v_cvt_pk_bf16_f32 v144, v152, v153
	v_cvt_pk_bf16_f32 v145, v154, v155
	v_cvt_pk_bf16_f32 v146, v190, v191
	v_cvt_pk_bf16_f32 v147, v2, v3
	global_store_dwordx4 v186, v[144:147], s[100:101] offset:256
	s_nop 1
	s_waitcnt vmcnt(9)
	v_lshlrev_b32_e32 v152, 16, v194
	v_and_b32_e32 v153, 0xffff0000, v194
	v_lshlrev_b32_e32 v154, 16, v195
	v_and_b32_e32 v155, 0xffff0000, v195
	v_lshlrev_b32_e32 v190, 16, v196
	v_and_b32_e32 v191, 0xffff0000, v196
	v_lshlrev_b32_e32 v2, 16, v197
	v_and_b32_e32 v3, 0xffff0000, v197
	global_load_dwordx4 v[194:197], v185, s[98:99] offset:256
	v_pk_mul_f32 v[152:153], v[56:57], v[152:153]
	v_pk_mul_f32 v[154:155], v[58:59], v[154:155]
	v_pk_mul_f32 v[190:191], v[52:53], v[190:191]
	v_pk_mul_f32 v[2:3], v[54:55], v[2:3]
	v_cvt_pk_bf16_f32 v144, v152, v153
	v_cvt_pk_bf16_f32 v145, v154, v155
	v_cvt_pk_bf16_f32 v146, v190, v191
	v_cvt_pk_bf16_f32 v147, v2, v3
	global_store_dwordx4 v187, v[144:147], s[100:101]
	s_nop 1
	s_waitcnt vmcnt(9)
; __device__ __forceinline__ unsigned cvt_pk(float lo, float hi) { f32x2_t v = {lo, hi}; bf16x2_t b = __builtin_convertvector(v, bf16x2_t); return __builtin_bit_cast(unsigned, b); }
; template <class Epi, class Sched, bool ALIGN_EPI = false, bool SP2 = false>
; __device__ __forceinline__ void gemm_phase(PG8_LAS unsigned char* lds, const Gemm g, const Sched& S, const Epi& E) {
;     ...
;         if (!keep_acc)
; #pragma unroll
;         for (int a = 0; a < 2; ++a)
; #pragma unroll
;             for (int b = 0; b < 2; ++b)
; #pragma unroll
;                 for (int m = 0; m < 4; ++m)
; #pragma unroll
;                     for (int n = 0; n < 2; ++n) acc[a][b][m][n] = (f32x4){0.f, 0.f, 0.f, 0.f};
;     __device__ __forceinline__ bool carry(f32x4 (&acc)[2][2][4][2], const Unit& u, int wr, int wc, int fr, int fq) const {
;     ...
;                     } else {
;                         float v[8];
; #pragma unroll
;                         for (int i = 0; i < 8; ++i) v[i] = acc[ai][bj][m][i >> 2][i & 3] * f[i];
;                         u32x4 w; w.x = cvt_pk(v[0], v[1]); w.y = cvt_pk(v[2], v[3]); w.z = cvt_pk(v[4], v[5]); w.w = cvt_pk(v[6], v[7]);
;                         *(u32x4*)(Mg + row * DM + c) = w;
;                     }
;                 }
;         return br < 2;
	v_lshlrev_b32_e32 v152, 16, v202
	v_and_b32_e32 v153, 0xffff0000, v202
	v_lshlrev_b32_e32 v154, 16, v203
	v_and_b32_e32 v155, 0xffff0000, v203
	v_lshlrev_b32_e32 v190, 16, v204
	v_and_b32_e32 v191, 0xffff0000, v204
	v_lshlrev_b32_e32 v2, 16, v205
	v_and_b32_e32 v3, 0xffff0000, v205
	v_pk_mul_f32 v[152:153], v[24:25], v[152:153]
	v_pk_mul_f32 v[154:155], v[26:27], v[154:155]
	v_pk_mul_f32 v[190:191], v[20:21], v[190:191]
	v_pk_mul_f32 v[2:3], v[22:23], v[2:3]
	v_cvt_pk_bf16_f32 v144, v152, v153
	v_cvt_pk_bf16_f32 v145, v154, v155
	v_cvt_pk_bf16_f32 v146, v190, v191
	v_cvt_pk_bf16_f32 v147, v2, v3
	global_store_dwordx4 v187, v[144:147], s[100:101] offset:256
	s_nop 1
	s_waitcnt vmcnt(8)
	v_lshlrev_b32_e32 v152, 16, v210
	v_and_b32_e32 v153, 0xffff0000, v210
	v_lshlrev_b32_e32 v154, 16, v211
	v_and_b32_e32 v155, 0xffff0000, v211
	v_lshlrev_b32_e32 v190, 16, v212
	v_and_b32_e32 v191, 0xffff0000, v212
	v_lshlrev_b32_e32 v2, 16, v213
	v_and_b32_e32 v3, 0xffff0000, v213
	v_pk_mul_f32 v[152:153], v[48:49], v[152:153]
	v_pk_mul_f32 v[154:155], v[50:51], v[154:155]
	v_pk_mul_f32 v[190:191], v[44:45], v[190:191]
	v_pk_mul_f32 v[2:3], v[46:47], v[2:3]
	v_cvt_pk_bf16_f32 v144, v152, v153
	v_cvt_pk_bf16_f32 v145, v154, v155
	v_cvt_pk_bf16_f32 v146, v190, v191
	v_cvt_pk_bf16_f32 v147, v2, v3
	global_store_dwordx4 v188, v[144:147], s[100:101]
	s_nop 1
	s_waitcnt vmcnt(7)
	v_lshlrev_b32_e32 v152, 16, v230
	v_and_b32_e32 v153, 0xffff0000, v230
	v_lshlrev_b32_e32 v154, 16, v231
	v_and_b32_e32 v155, 0xffff0000, v231
	v_lshlrev_b32_e32 v190, 16, v232
	v_and_b32_e32 v191, 0xffff0000, v232
	v_lshlrev_b32_e32 v2, 16, v233
	v_and_b32_e32 v3, 0xffff0000, v233
	v_pk_mul_f32 v[152:153], v[16:17], v[152:153]
	v_pk_mul_f32 v[154:155], v[18:19], v[154:155]
	v_pk_mul_f32 v[190:191], v[12:13], v[190:191]
	v_pk_mul_f32 v[2:3], v[14:15], v[2:3]
	v_cvt_pk_bf16_f32 v144, v152, v153
	v_cvt_pk_bf16_f32 v145, v154, v155
	v_cvt_pk_bf16_f32 v146, v190, v191
	v_cvt_pk_bf16_f32 v147, v2, v3
	global_store_dwordx4 v188, v[144:147], s[100:101] offset:256
	s_nop 1
	s_waitcnt vmcnt(6)
	v_lshlrev_b32_e32 v152, 16, v238
	v_and_b32_e32 v153, 0xffff0000, v238
	v_lshlrev_b32_e32 v154, 16, v239
	v_and_b32_e32 v155, 0xffff0000, v239
	v_lshlrev_b32_e32 v190, 16, v240
	v_and_b32_e32 v191, 0xffff0000, v240
	v_lshlrev_b32_e32 v2, 16, v241
	v_and_b32_e32 v3, 0xffff0000, v241
	v_pk_mul_f32 v[152:153], v[40:41], v[152:153]
	v_pk_mul_f32 v[154:155], v[42:43], v[154:155]
	v_pk_mul_f32 v[190:191], v[36:37], v[190:191]
	v_pk_mul_f32 v[2:3], v[38:39], v[2:3]
	v_cvt_pk_bf16_f32 v144, v152, v153
	v_cvt_pk_bf16_f32 v145, v154, v155
	v_cvt_pk_bf16_f32 v146, v190, v191
	v_cvt_pk_bf16_f32 v147, v2, v3
	global_store_dwordx4 v189, v[144:147], s[100:101]
	s_nop 1
	s_waitcnt vmcnt(5)
	v_lshlrev_b32_e32 v152, 16, v194
	v_and_b32_e32 v153, 0xffff0000, v194
	v_lshlrev_b32_e32 v154, 16, v195
	v_and_b32_e32 v155, 0xffff0000, v195
	v_lshlrev_b32_e32 v190, 16, v196
	v_and_b32_e32 v191, 0xffff0000, v196
	v_lshlrev_b32_e32 v2, 16, v197
	v_and_b32_e32 v3, 0xffff0000, v197
	v_pk_mul_f32 v[152:153], v[8:9], v[152:153]
	v_pk_mul_f32 v[154:155], v[10:11], v[154:155]
	v_pk_mul_f32 v[190:191], v[4:5], v[190:191]
	v_pk_mul_f32 v[2:3], v[6:7], v[2:3]
	v_cvt_pk_bf16_f32 v144, v152, v153
	v_cvt_pk_bf16_f32 v145, v154, v155
	v_cvt_pk_bf16_f32 v146, v190, v191
	v_cvt_pk_bf16_f32 v147, v2, v3
	global_store_dwordx4 v189, v[144:147], s[100:101] offset:256
	s_nop 1
.Lmg_done:
	s_andn2_b64 vcc, exec, s[38:39]
	s_mov_b64 s[6:7], -1
	s_cbranch_vccnz .LBB0_29
.LBB0_106:
	s_and_b64 vcc, exec, s[40:41]
	s_cbranch_vccnz .LBB0_108
	v_mov_b32_e32 v2, v1
	v_mov_b32_e32 v3, v1
	v_mov_b32_e32 v0, v1
	v_mov_b64_e32 v[6:7], v[2:3]
	v_mov_b64_e32 v[10:11], v[2:3]
	v_mov_b64_e32 v[14:15], v[2:3]
	v_mov_b64_e32 v[18:19], v[2:3]
	v_mov_b64_e32 v[22:23], v[2:3]
	v_mov_b64_e32 v[26:27], v[2:3]
	v_mov_b64_e32 v[30:31], v[2:3]
	v_mov_b64_e32 v[34:35], v[2:3]
	v_mov_b64_e32 v[38:39], v[2:3]
	v_mov_b64_e32 v[42:43], v[2:3]
	v_mov_b64_e32 v[46:47], v[2:3]
	v_mov_b64_e32 v[50:51], v[2:3]
	v_mov_b64_e32 v[54:55], v[2:3]
	v_mov_b64_e32 v[58:59], v[2:3]
	v_mov_b64_e32 v[62:63], v[2:3]
	v_mov_b64_e32 v[66:67], v[2:3]
	v_mov_b64_e32 v[70:71], v[2:3]
	v_mov_b64_e32 v[74:75], v[2:3]
	v_mov_b64_e32 v[78:79], v[2:3]
	v_mov_b64_e32 v[82:83], v[2:3]
	v_mov_b64_e32 v[86:87], v[2:3]
	v_mov_b64_e32 v[90:91], v[2:3]
	v_mov_b64_e32 v[94:95], v[2:3]
	v_mov_b64_e32 v[98:99], v[2:3]
	v_mov_b64_e32 v[102:103], v[2:3]
	v_mov_b64_e32 v[106:107], v[2:3]
	v_mov_b64_e32 v[110:111], v[2:3]
	v_mov_b64_e32 v[114:115], v[2:3]
	v_mov_b64_e32 v[118:119], v[2:3]
	v_mov_b64_e32 v[122:123], v[2:3]
	v_mov_b64_e32 v[126:127], v[2:3]
	v_mov_b64_e32 v[130:131], v[2:3]
	v_mov_b64_e32 v[4:5], v[0:1]
	v_mov_b64_e32 v[8:9], v[0:1]
	v_mov_b64_e32 v[12:13], v[0:1]
	v_mov_b64_e32 v[16:17], v[0:1]
	v_mov_b64_e32 v[20:21], v[0:1]
	v_mov_b64_e32 v[24:25], v[0:1]
	v_mov_b64_e32 v[28:29], v[0:1]
	v_mov_b64_e32 v[32:33], v[0:1]
	v_mov_b64_e32 v[36:37], v[0:1]
	v_mov_b64_e32 v[40:41], v[0:1]
	v_mov_b64_e32 v[44:45], v[0:1]
	v_mov_b64_e32 v[48:49], v[0:1]
	v_mov_b64_e32 v[52:53], v[0:1]
	v_mov_b64_e32 v[56:57], v[0:1]
	v_mov_b64_e32 v[60:61], v[0:1]
	v_mov_b64_e32 v[64:65], v[0:1]
	v_mov_b64_e32 v[68:69], v[0:1]
	v_mov_b64_e32 v[72:73], v[0:1]
	v_mov_b64_e32 v[76:77], v[0:1]
	v_mov_b64_e32 v[80:81], v[0:1]
	v_mov_b64_e32 v[84:85], v[0:1]
	v_mov_b64_e32 v[88:89], v[0:1]
	v_mov_b64_e32 v[92:93], v[0:1]
	v_mov_b64_e32 v[96:97], v[0:1]
	v_mov_b64_e32 v[100:101], v[0:1]
	v_mov_b64_e32 v[104:105], v[0:1]
	v_mov_b64_e32 v[108:109], v[0:1]
	v_mov_b64_e32 v[112:113], v[0:1]
	v_mov_b64_e32 v[116:117], v[0:1]
	v_mov_b64_e32 v[120:121], v[0:1]
	v_mov_b64_e32 v[124:125], v[0:1]
	v_mov_b64_e32 v[128:129], v[0:1]

.LBB0_308:
	s_cmp_eq_u64 s[44:45], 0
	s_cselect_b64 s[40:41], -1, 0
	s_cmp_lg_u64 s[44:45], 0
	s_cselect_b64 s[42:43], -1, 0
	s_ff1_i32_b64 s6, s[44:45]
	s_and_b64 vcc, exec, s[40:41]
	s_cbranch_vccnz .LBB0_310
	v_lshl_add_u32 v0, s6, 6, v173
	v_min_i32_e32 v0, 0xfff, v0
	v_mad_i64_i32 v[2:3], s[38:39], v0, s23, v[170:171]
	v_lshl_add_u64 v[2:3], v[2:3], 1, s[26:27]
	global_load_dwordx4 v[6:9], v[2:3], off offset:1536
	s_nop 0
	global_load_dwordx4 v[2:5], v[2:3], off offset:1792

.LBB0_318:
	s_cmp_lt_i32 s18, 0
	s_cbranch_scc1 .LBB0_320
	v_add_u32_e32 v0, v172, v174
	s_cmp_lg_u64 s[42:43], 0
	s_cbranch_scc0 .Lsel_ev_w0
	s_waitcnt vmcnt(2)
	s_branch .Lsel_ev_st

.Lsel_ev_st:
	ds_write_b128 v188, v[152:155] offset:9216
	ds_write_b128 v0, v[156:159] offset:30720

.LBB0_331:
	s_andn2_b64 vcc, exec, s[42:43]
	s_cbranch_vccnz .LBB0_307
	s_cmp_lg_u64 s[46:47], 0
	s_cbranch_scc1 .Lsel_od_w0
	s_waitcnt vmcnt(2)
	s_branch .Lsel_od_st

.Lsel_od_st:
	ds_write_b128 v175, v[6:9]
	ds_write_b128 v176, v[2:5] offset:18432
	s_branch .LBB0_307

.LBB0_342:
	s_cmp_eq_u64 s[44:45], 0
	s_cselect_b64 s[40:41], -1, 0
	s_cmp_lg_u64 s[44:45], 0
	s_cselect_b64 s[42:43], -1, 0
	s_ff1_i32_b64 s29, s[44:45]
	s_and_b64 vcc, exec, s[40:41]
	s_cbranch_vccnz .LBB0_344
	v_lshl_add_u32 v0, s29, 6, v182
	v_min_i32_e32 v0, 0xfff, v0
	v_mad_i64_i32 v[2:3], s[6:7], v0, s23, v[160:161]
	v_lshl_add_u64 v[2:3], v[2:3], 1, s[26:27]
	global_load_dwordx4 v[6:9], v[2:3], off offset:2048
	s_nop 0
	global_load_dwordx4 v[2:5], v[2:3], off offset:2304

; __device__ __forceinline__ unsigned cvt_pk(float lo, float hi) { f32x2_t v = {lo, hi}; bf16x2_t b = __builtin_convertvector(v, bf16x2_t); return __builtin_bit_cast(unsigned, b); }
; __device__ __forceinline__ f32x16 mfma32(bf16x8 a, bf16x8 b, f32x16 c) { return __builtin_amdgcn_mfma_f32_32x32x16_bf16(a, b, c, 0, 0, 0); }
; __device__ __forceinline__ s16x4 tr16(lptr p) { return __builtin_bit_cast(s16x4, __builtin_amdgcn_ds_read_tr16_b64_v4i16((LAS v4i16_t*)p)); }
; template <int MODE> ...
;     ...
;         if (MODE != MODE_CMP1) {
;             bf16x8 pf[4];
; #pragma unroll
;             for (int ks = 0; ks < 4; ++ks) {
;                 const int hb = 8 * (ks & 1); u32x4 w;
;                 if (ks >> 1) { w.x = cvt_pk(s1[hb], s1[hb + 1]); w.y = cvt_pk(s1[hb + 2], s1[hb + 3]); w.z = cvt_pk(s1[hb + 4], s1[hb + 5]); w.w = cvt_pk(s1[hb + 6], s1[hb + 7]); }
;                 else { w.x = cvt_pk(s0[hb], s0[hb + 1]); w.y = cvt_pk(s0[hb + 2], s0[hb + 3]); w.z = cvt_pk(s0[hb + 4], s0[hb + 5]); w.w = cvt_pk(s0[hb + 6], s0[hb + 7]); }
;                 pf[ks] = __builtin_bit_cast(bf16x8, w);
;             }
;             const lptr vb_ = Vt + (4 * hl + q4) * VP + 32 * blk + 8 * p4;
; #pragma unroll
;             for (int c_ = 0; c_ < 2; ++c_)
; #pragma unroll
;                 for (int ks_ = 0; ks_ < 4; ++ks_) {
;                     const s16x4 lo_ = tr16(vb_ + (16 * ks_) * VP + 64 * c_), hi_ = tr16(vb_ + (16 * ks_ + 8) * VP + 64 * c_);
;                     const bf16x8 vf_ = {lo_[0], lo_[1], lo_[2], lo_[3], hi_[0], hi_[1], hi_[2], hi_[3]};
;                     o[c_] = mfma32(vf_, pf[ks_], o[c_]);
;                 }
.LBB0_384:
	v_exp_f32_e32 v0, v96
	v_exp_f32_e32 v14, v97
	v_exp_f32_e32 v15, v98
	v_exp_f32_e32 v96, v99
	v_exp_f32_e32 v97, v100
	v_exp_f32_e32 v100, v84
	v_exp_f32_e32 v84, v101
	v_exp_f32_e32 v101, v85
	v_exp_f32_e32 v85, v102
	v_exp_f32_e32 v102, v86
	v_exp_f32_e32 v86, v103
	v_cvt_pk_bf16_f32 v118, v0, v14
	v_cvt_pk_bf16_f32 v119, v15, v96
	v_cvt_pk_bf16_f32 v120, v97, v84
	v_cvt_pk_bf16_f32 v121, v85, v86
	v_exp_f32_e32 v103, v87
	v_exp_f32_e32 v87, v104
	s_waitcnt lgkmcnt(0)
	s_waitcnt lgkmcnt(0)
	v_mfma_f32_32x32x16_bf16 v[32:47], v[196:199], v[118:121], v[32:47]
	v_exp_f32_e32 v104, v88
	v_exp_f32_e32 v88, v105
	v_exp_f32_e32 v105, v89
	v_exp_f32_e32 v89, v106
	v_exp_f32_e32 v106, v90
	v_exp_f32_e32 v90, v107
	v_exp_f32_e32 v107, v91
	v_exp_f32_e32 v91, v108
	v_exp_f32_e32 v108, v92
	v_exp_f32_e32 v92, v109
	v_exp_f32_e32 v109, v93
	v_exp_f32_e32 v93, v110
	v_exp_f32_e32 v110, v94
	v_exp_f32_e32 v94, v111
	v_cvt_pk_bf16_f32 v114, v87, v88
	v_cvt_pk_bf16_f32 v115, v89, v90
	v_cvt_pk_bf16_f32 v116, v91, v92
	v_cvt_pk_bf16_f32 v117, v93, v94
	v_exp_f32_e32 v112, v80
	v_exp_f32_e32 v113, v81
	v_mfma_f32_32x32x16_bf16 v[32:47], v[200:203], v[114:117], v[32:47]
	v_exp_f32_e32 v98, v82
	v_exp_f32_e32 v99, v83
	v_cvt_pk_bf16_f32 v80, v112, v113
	v_cvt_pk_bf16_f32 v82, v100, v101
	v_cvt_pk_bf16_f32 v81, v98, v99
	v_cvt_pk_bf16_f32 v83, v102, v103
	v_exp_f32_e32 v95, v95
	v_cvt_pk_bf16_f32 v10, v104, v105
	v_mfma_f32_32x32x16_bf16 v[32:47], v[204:207], v[80:83], v[32:47]
	v_cvt_pk_bf16_f32 v11, v106, v107
	v_cvt_pk_bf16_f32 v12, v108, v109
	v_cvt_pk_bf16_f32 v13, v110, v95
	s_cmp_lt_i32 s18, 0
	s_nop 1
	v_mfma_f32_32x32x16_bf16 v[32:47], v[208:211], v[10:13], v[32:47]
	v_mfma_f32_32x32x16_bf16 v[16:31], v[238:241], v[118:121], v[16:31]
	v_mfma_f32_32x32x16_bf16 v[16:31], v[242:245], v[114:117], v[16:31]
	v_mfma_f32_32x32x16_bf16 v[16:31], v[246:249], v[80:83], v[16:31]
	v_mfma_f32_32x32x16_bf16 v[16:31], v[234:237], v[10:13], v[16:31]
	s_cbranch_scc1 .LBB0_386
	v_add_u32_e32 v10, v144, v183
	s_cmp_lg_u64 s[42:43], 0
	s_cbranch_scc0 .Lwin_ev_w0
	s_waitcnt vmcnt(2)
	s_branch .Lwin_ev_st

.Lwin_ev_st:
	ds_write_b128 v189, v[152:155] offset:9216
	ds_write_b128 v10, v[156:159] offset:30720

; __device__ __forceinline__ unsigned cvt_pk(float lo, float hi) { f32x2_t v = {lo, hi}; bf16x2_t b = __builtin_convertvector(v, bf16x2_t); return __builtin_bit_cast(unsigned, b); }
; __device__ __forceinline__ f32x16 mfma32(bf16x8 a, bf16x8 b, f32x16 c) { return __builtin_amdgcn_mfma_f32_32x32x16_bf16(a, b, c, 0, 0, 0); }
; __device__ __forceinline__ s16x4 tr16(lptr p) { return __builtin_bit_cast(s16x4, __builtin_amdgcn_ds_read_tr16_b64_v4i16((LAS v4i16_t*)p)); }
; template <int MODE> ...
;     ...
;         if (MODE != MODE_CMP1) {
;             bf16x8 pf[4];
; #pragma unroll
;             for (int ks = 0; ks < 4; ++ks) {
;                 const int hb = 8 * (ks & 1); u32x4 w;
;                 if (ks >> 1) { w.x = cvt_pk(s1[hb], s1[hb + 1]); w.y = cvt_pk(s1[hb + 2], s1[hb + 3]); w.z = cvt_pk(s1[hb + 4], s1[hb + 5]); w.w = cvt_pk(s1[hb + 6], s1[hb + 7]); }
;                 else { w.x = cvt_pk(s0[hb], s0[hb + 1]); w.y = cvt_pk(s0[hb + 2], s0[hb + 3]); w.z = cvt_pk(s0[hb + 4], s0[hb + 5]); w.w = cvt_pk(s0[hb + 6], s0[hb + 7]); }
;                 pf[ks] = __builtin_bit_cast(bf16x8, w);
;             }
;             const lptr vb_ = Vt + (4 * hl + q4) * VP + 32 * blk + 8 * p4;
; #pragma unroll
;             for (int c_ = 0; c_ < 2; ++c_)
; #pragma unroll
;                 for (int ks_ = 0; ks_ < 4; ++ks_) {
;                     const s16x4 lo_ = tr16(vb_ + (16 * ks_) * VP + 64 * c_), hi_ = tr16(vb_ + (16 * ks_ + 8) * VP + 64 * c_);
;                     const bf16x8 vf_ = {lo_[0], lo_[1], lo_[2], lo_[3], hi_[0], hi_[1], hi_[2], hi_[3]};
;                     o[c_] = mfma32(vf_, pf[ks_], o[c_]);
;                 }
.LBB0_428:
	v_exp_f32_e32 v0, v96
	v_exp_f32_e32 v14, v97
	v_exp_f32_e32 v15, v98
	v_exp_f32_e32 v68, v99
	v_exp_f32_e32 v69, v100
	v_exp_f32_e32 v70, v101
	v_exp_f32_e32 v71, v102
	v_exp_f32_e32 v72, v103
	v_exp_f32_e32 v75, v106
	v_exp_f32_e32 v76, v107
	v_exp_f32_e32 v77, v108
	v_exp_f32_e32 v78, v109
	v_exp_f32_e32 v73, v104
	v_exp_f32_e32 v74, v105
	v_cvt_pk_bf16_f32 v102, v0, v14
	v_cvt_pk_bf16_f32 v103, v15, v68
	v_cvt_pk_bf16_f32 v104, v69, v70
	v_cvt_pk_bf16_f32 v105, v71, v72
	v_exp_f32_e32 v96, v80
	v_exp_f32_e32 v79, v110
	s_waitcnt lgkmcnt(0)
	s_waitcnt lgkmcnt(0)
	v_mfma_f32_32x32x16_bf16 v[32:47], v[196:199], v[102:105], v[32:47]
	v_exp_f32_e32 v80, v111
	v_cvt_pk_bf16_f32 v98, v73, v74
	v_cvt_pk_bf16_f32 v99, v75, v76
	v_cvt_pk_bf16_f32 v100, v77, v78
	v_cvt_pk_bf16_f32 v101, v79, v80
	v_exp_f32_e32 v81, v81
	v_exp_f32_e32 v82, v82
	v_mfma_f32_32x32x16_bf16 v[32:47], v[200:203], v[98:101], v[32:47]
	v_exp_f32_e32 v83, v83
	v_exp_f32_e32 v84, v84
	v_exp_f32_e32 v85, v85
	v_exp_f32_e32 v86, v86
	v_exp_f32_e32 v87, v87
	v_cvt_pk_bf16_f32 v64, v96, v81
	v_cvt_pk_bf16_f32 v65, v82, v83
	v_cvt_pk_bf16_f32 v66, v84, v85
	v_cvt_pk_bf16_f32 v67, v86, v87
	v_exp_f32_e32 v88, v88
	v_exp_f32_e32 v89, v89
	v_mfma_f32_32x32x16_bf16 v[32:47], v[204:207], v[64:67], v[32:47]
	v_exp_f32_e32 v90, v90
	v_exp_f32_e32 v91, v91
	v_exp_f32_e32 v92, v92
	v_exp_f32_e32 v93, v93
	v_exp_f32_e32 v94, v94
	v_exp_f32_e32 v95, v95
	v_cvt_pk_bf16_f32 v10, v88, v89
	v_cvt_pk_bf16_f32 v11, v90, v91
	v_cvt_pk_bf16_f32 v12, v92, v93
	v_cvt_pk_bf16_f32 v13, v94, v95
	s_andn2_b64 vcc, exec, s[42:43]
	s_nop 1
	v_mfma_f32_32x32x16_bf16 v[32:47], v[208:211], v[10:13], v[32:47]
	v_mfma_f32_32x32x16_bf16 v[16:31], v[238:241], v[102:105], v[16:31]
	v_mfma_f32_32x32x16_bf16 v[16:31], v[242:245], v[98:101], v[16:31]
	v_mfma_f32_32x32x16_bf16 v[16:31], v[246:249], v[64:67], v[16:31]
	v_mfma_f32_32x32x16_bf16 v[16:31], v[234:237], v[10:13], v[16:31]
	s_cbranch_vccnz .LBB0_341
	s_cmp_lg_u64 s[46:47], 0
	s_cbranch_scc1 .Lwin_od_w0
	s_waitcnt vmcnt(2)
	s_branch .Lwin_od_st

.Lwin_od_st:
	ds_write_b128 v184, v[6:9]
	ds_write_b128 v185, v[2:5] offset:18432
	s_branch .LBB0_341

;     __device__ __forceinline__ void operator()(const f32x4 (&acc)[2][2][4][2], const Unit& u, int wr, int wc, int fr, int fq) const {
;         const int row0 = u.pm * 256 + wr * 64 + fr, col0 = u.pn * 256 + wc * 32 + 8 * fq;
; #pragma unroll
;         for (int bj = 0; bj < 2; ++bj) {
;             const int c = col0 + bj * 128;
;             f32x4 g0 = {1.f, 1.f, 1.f, 1.f}, g1 = g0, b0 = {0.f, 0.f, 0.f, 0.f}, b1 = b0;
;             if (lng) { g0 = *(const f32x4*)(lng + c); g1 = *(const f32x4*)(lng + c + 4); b0 = *(const f32x4*)(lnb + c); b1 = *(const f32x4*)(lnb + c + 4); }
;             g0 = g0 * ca; g1 = g1 * ca; b0 = b0 * ca; b1 = b1 * ca;
; #pragma unroll
;             for (int ai = 0; ai < 2; ++ai)
; #pragma unroll
;                 for (int m = 0; m < 4; ++m) {
;                     const int row = row0 + ai * 128 + m * 16;
;                     float mean = 0.f, rstd = 1.f;
;                     if (lng) { const float2 st = *(const float2*)(stats + 2 * (size_t)row); mean = st.x; rstd = st.y; }
;                     float* p = X + (size_t)row * DM + c;
;                     f32x4 x0 = *(const f32x4*)p, x1 = *(const f32x4*)(p + 4);
.LBB0_820:
	v_lshl_or_b32 v154, s13, 8, v186
	v_lshl_add_u32 v178, s18, 8, v167
	s_add_u32 s40, s94, 0x80000
	s_addc_u32 s41, s95, 0
	v_lshlrev_b32_e32 v155, 2, v154
	v_lshlrev_b32_e32 v179, 3, v178
	v_lshlrev_b32_e32 v180, 12, v178
	v_add_u32_e32 v180, v180, v155
	v_add_u32_e32 v182, 0x10000, v180
	v_add_u32_e32 v183, 0x20000, v180
	v_add_u32_e32 v184, 0x30000, v180
	s_andn2_b64 vcc, exec, s[46:47]
	s_cbranch_vccnz .Lres_nolng
	global_load_dwordx4 v[144:147], v155, s[30:31]
	global_load_dwordx4 v[148:151], v155, s[30:31] offset:16
	global_load_dwordx4 v[156:159], v155, s[42:43]
	global_load_dwordx4 v[170:173], v155, s[42:43] offset:16
	global_load_dwordx4 v[174:177], v155, s[30:31] offset:512
	global_load_dwordx4 v[188:191], v155, s[30:31] offset:528
	global_load_dwordx4 v[194:197], v155, s[42:43] offset:512
	global_load_dwordx4 v[198:201], v155, s[42:43] offset:528
	s_branch .Lres_gbdone

;     __device__ __forceinline__ void operator()(const f32x4 (&acc)[2][2][4][2], const Unit& u, int wr, int wc, int fr, int fq) const {
;     ...
;         for (int bj = 0; bj < 2; ++bj) {
;             const int c = col0 + bj * 128;
;             f32x4 g0 = {1.f, 1.f, 1.f, 1.f}, g1 = g0, b0 = {0.f, 0.f, 0.f, 0.f}, b1 = b0;
;             if (lng) { g0 = *(const f32x4*)(lng + c); g1 = *(const f32x4*)(lng + c + 4); b0 = *(const f32x4*)(lnb + c); b1 = *(const f32x4*)(lnb + c + 4); }
;             g0 = g0 * ca; g1 = g1 * ca; b0 = b0 * ca; b1 = b1 * ca;
; #pragma unroll
;             for (int ai = 0; ai < 2; ++ai)
; #pragma unroll
;                 for (int m = 0; m < 4; ++m) {
;                     const int row = row0 + ai * 128 + m * 16;
;                     float mean = 0.f, rstd = 1.f;
;                     if (lng) { const float2 st = *(const float2*)(stats + 2 * (size_t)row); mean = st.x; rstd = st.y; }
;                     float* p = X + (size_t)row * DM + c;
;                     f32x4 x0 = *(const f32x4*)p, x1 = *(const f32x4*)(p + 4);
;                     x0 = (x0 - mean) * rstd * g0 + b0 + acc[ai][bj][m][0] * cb; x1 = (x1 - mean) * rstd * g1 + b1 + acc[ai][bj][m][1] * cb;
;                     *(f32x4*)p = x0; *(f32x4*)(p + 4) = x1;
;                     if (m & 1) asm volatile("" ::: "memory");
;                 }
.Lres_noscale:
	v_cndmask_b32_e64 v152, 0, v152, s[46:47]
	v_pk_add_f32 v[202:203], v[202:203], v[152:153] op_sel_hi:[1,0] neg_lo:[0,1] neg_hi:[0,1]
	v_pk_add_f32 v[204:205], v[204:205], v[152:153] op_sel_hi:[1,0] neg_lo:[0,1] neg_hi:[0,1]
	v_pk_add_f32 v[206:207], v[206:207], v[152:153] op_sel_hi:[1,0] neg_lo:[0,1] neg_hi:[0,1]
	v_pk_add_f32 v[208:209], v[208:209], v[152:153] op_sel_hi:[1,0] neg_lo:[0,1] neg_hi:[0,1]
	v_cndmask_b32_e64 v152, 1.0, v153, s[46:47]
	v_pk_mul_f32 v[202:203], v[152:153], v[202:203] op_sel_hi:[0,1]
	v_pk_mul_f32 v[204:205], v[152:153], v[204:205] op_sel_hi:[0,1]
	v_pk_mul_f32 v[206:207], v[152:153], v[206:207] op_sel_hi:[0,1]
	v_pk_mul_f32 v[208:209], v[152:153], v[208:209] op_sel_hi:[0,1]
	v_pk_fma_f32 v[202:203], v[144:145], v[202:203], v[156:157]
	v_pk_fma_f32 v[204:205], v[146:147], v[204:205], v[158:159]
	v_pk_fma_f32 v[206:207], v[148:149], v[206:207], v[170:171]
	v_pk_fma_f32 v[208:209], v[150:151], v[208:209], v[172:173]
	v_pk_fma_f32 v[126:127], v[138:139], v[126:127], v[202:203]
	v_pk_fma_f32 v[128:129], v[138:139], v[128:129], v[204:205]
	v_pk_fma_f32 v[122:123], v[138:139], v[122:123], v[206:207]
	v_pk_fma_f32 v[124:125], v[138:139], v[124:125], v[208:209]
	global_store_dwordx4 v180, v[126:129], s[94:95]
	global_store_dwordx4 v180, v[122:125], s[94:95] offset:16
	global_load_dwordx2 v[152:153], v179, s[96:97] offset:1024
	global_load_dwordx4 v[202:205], v180, s[40:41]
	global_load_dwordx4 v[206:209], v180, s[40:41] offset:16
	s_waitcnt vmcnt(11)
	v_cndmask_b32_e64 v160, 0, v160, s[46:47]
	v_pk_add_f32 v[210:211], v[210:211], v[160:161] op_sel_hi:[1,0] neg_lo:[0,1] neg_hi:[0,1]
	v_pk_add_f32 v[212:213], v[212:213], v[160:161] op_sel_hi:[1,0] neg_lo:[0,1] neg_hi:[0,1]
	v_pk_add_f32 v[226:227], v[226:227], v[160:161] op_sel_hi:[1,0] neg_lo:[0,1] neg_hi:[0,1]
	v_pk_add_f32 v[228:229], v[228:229], v[160:161] op_sel_hi:[1,0] neg_lo:[0,1] neg_hi:[0,1]
	v_cndmask_b32_e64 v160, 1.0, v161, s[46:47]
	v_pk_mul_f32 v[210:211], v[160:161], v[210:211] op_sel_hi:[0,1]
	v_pk_mul_f32 v[212:213], v[160:161], v[212:213] op_sel_hi:[0,1]
	v_pk_mul_f32 v[226:227], v[160:161], v[226:227] op_sel_hi:[0,1]
	v_pk_mul_f32 v[228:229], v[160:161], v[228:229] op_sel_hi:[0,1]
	v_pk_fma_f32 v[210:211], v[144:145], v[210:211], v[156:157]
	v_pk_fma_f32 v[212:213], v[146:147], v[212:213], v[158:159]
	v_pk_fma_f32 v[226:227], v[148:149], v[226:227], v[170:171]
	v_pk_fma_f32 v[228:229], v[150:151], v[228:229], v[172:173]
	v_pk_fma_f32 v[118:119], v[138:139], v[118:119], v[210:211]
	v_pk_fma_f32 v[120:121], v[138:139], v[120:121], v[212:213]
	v_pk_fma_f32 v[114:115], v[138:139], v[114:115], v[226:227]
	v_pk_fma_f32 v[116:117], v[138:139], v[116:117], v[228:229]
	global_store_dwordx4 v182, v[118:121], s[94:95]
	global_store_dwordx4 v182, v[114:117], s[94:95] offset:16
	global_load_dwordx2 v[160:161], v179, s[96:97] offset:1152
	global_load_dwordx4 v[210:213], v182, s[40:41]
	global_load_dwordx4 v[226:229], v182, s[40:41] offset:16
	s_waitcnt vmcnt(13)
	v_cndmask_b32_e64 v216, 0, v216, s[46:47]
	v_pk_add_f32 v[230:231], v[230:231], v[216:217] op_sel_hi:[1,0] neg_lo:[0,1] neg_hi:[0,1]
	v_pk_add_f32 v[232:233], v[232:233], v[216:217] op_sel_hi:[1,0] neg_lo:[0,1] neg_hi:[0,1]
	v_pk_add_f32 v[234:235], v[234:235], v[216:217] op_sel_hi:[1,0] neg_lo:[0,1] neg_hi:[0,1]
	v_pk_add_f32 v[236:237], v[236:237], v[216:217] op_sel_hi:[1,0] neg_lo:[0,1] neg_hi:[0,1]
	v_cndmask_b32_e64 v216, 1.0, v217, s[46:47]
	v_pk_mul_f32 v[230:231], v[216:217], v[230:231] op_sel_hi:[0,1]
	v_pk_mul_f32 v[232:233], v[216:217], v[232:233] op_sel_hi:[0,1]
	v_pk_mul_f32 v[234:235], v[216:217], v[234:235] op_sel_hi:[0,1]
	v_pk_mul_f32 v[236:237], v[216:217], v[236:237] op_sel_hi:[0,1]
	v_pk_fma_f32 v[230:231], v[144:145], v[230:231], v[156:157]
	v_pk_fma_f32 v[232:233], v[146:147], v[232:233], v[158:159]
	v_pk_fma_f32 v[234:235], v[148:149], v[234:235], v[170:171]
	v_pk_fma_f32 v[236:237], v[150:151], v[236:237], v[172:173]
	v_pk_fma_f32 v[110:111], v[138:139], v[110:111], v[230:231]
	v_pk_fma_f32 v[112:113], v[138:139], v[112:113], v[232:233]
	v_pk_fma_f32 v[106:107], v[138:139], v[106:107], v[234:235]
	v_pk_fma_f32 v[108:109], v[138:139], v[108:109], v[236:237]
	global_store_dwordx4 v183, v[110:113], s[94:95]
	global_store_dwordx4 v183, v[106:109], s[94:95] offset:16
	global_load_dwordx2 v[216:217], v179, s[96:97] offset:1280
	global_load_dwordx4 v[230:233], v183, s[40:41]
	global_load_dwordx4 v[234:237], v183, s[40:41] offset:16
	s_waitcnt vmcnt(15)
	v_cndmask_b32_e64 v246, 0, v246, s[46:47]
	v_pk_add_f32 v[238:239], v[238:239], v[246:247] op_sel_hi:[1,0] neg_lo:[0,1] neg_hi:[0,1]
	v_pk_add_f32 v[240:241], v[240:241], v[246:247] op_sel_hi:[1,0] neg_lo:[0,1] neg_hi:[0,1]
	v_pk_add_f32 v[242:243], v[242:243], v[246:247] op_sel_hi:[1,0] neg_lo:[0,1] neg_hi:[0,1]
	v_pk_add_f32 v[244:245], v[244:245], v[246:247] op_sel_hi:[1,0] neg_lo:[0,1] neg_hi:[0,1]
	v_cndmask_b32_e64 v246, 1.0, v247, s[46:47]
	v_pk_mul_f32 v[238:239], v[246:247], v[238:239] op_sel_hi:[0,1]
	v_pk_mul_f32 v[240:241], v[246:247], v[240:241] op_sel_hi:[0,1]
	v_pk_mul_f32 v[242:243], v[246:247], v[242:243] op_sel_hi:[0,1]
	v_pk_mul_f32 v[244:245], v[246:247], v[244:245] op_sel_hi:[0,1]
	v_pk_fma_f32 v[238:239], v[144:145], v[238:239], v[156:157]
	v_pk_fma_f32 v[240:241], v[146:147], v[240:241], v[158:159]
	v_pk_fma_f32 v[242:243], v[148:149], v[242:243], v[170:171]
	v_pk_fma_f32 v[244:245], v[150:151], v[244:245], v[172:173]
	v_pk_fma_f32 v[102:103], v[138:139], v[102:103], v[238:239]
	v_pk_fma_f32 v[104:105], v[138:139], v[104:105], v[240:241]
	v_pk_fma_f32 v[98:99], v[138:139], v[98:99], v[242:243]
	v_pk_fma_f32 v[100:101], v[138:139], v[100:101], v[244:245]
	global_store_dwordx4 v184, v[102:105], s[94:95]
	global_store_dwordx4 v184, v[98:101], s[94:95] offset:16
	global_load_dwordx2 v[246:247], v179, s[96:97] offset:1408
	global_load_dwordx4 v[238:241], v184, s[40:41]
	global_load_dwordx4 v[242:245], v184, s[40:41] offset:16
	s_waitcnt vmcnt(15)
;     __device__ __forceinline__ void operator()(const f32x4 (&acc)[2][2][4][2], const Unit& u, int wr, int wc, int fr, int fq) const {
;     ...
;         for (int bj = 0; bj < 2; ++bj) {
;             const int c = col0 + bj * 128;
;             f32x4 g0 = {1.f, 1.f, 1.f, 1.f}, g1 = g0, b0 = {0.f, 0.f, 0.f, 0.f}, b1 = b0;
;             if (lng) { g0 = *(const f32x4*)(lng + c); g1 = *(const f32x4*)(lng + c + 4); b0 = *(const f32x4*)(lnb + c); b1 = *(const f32x4*)(lnb + c + 4); }
;             g0 = g0 * ca; g1 = g1 * ca; b0 = b0 * ca; b1 = b1 * ca;
; #pragma unroll
;             for (int ai = 0; ai < 2; ++ai)
; #pragma unroll
;                 for (int m = 0; m < 4; ++m) {
;                     const int row = row0 + ai * 128 + m * 16;
;                     float mean = 0.f, rstd = 1.f;
;                     if (lng) { const float2 st = *(const float2*)(stats + 2 * (size_t)row); mean = st.x; rstd = st.y; }
;                     float* p = X + (size_t)row * DM + c;
;                     f32x4 x0 = *(const f32x4*)p, x1 = *(const f32x4*)(p + 4);
;                     x0 = (x0 - mean) * rstd * g0 + b0 + acc[ai][bj][m][0] * cb; x1 = (x1 - mean) * rstd * g1 + b1 + acc[ai][bj][m][1] * cb;
;                     *(f32x4*)p = x0; *(f32x4*)(p + 4) = x1;
;                     if (m & 1) asm volatile("" ::: "memory");
;                 }
	v_cndmask_b32_e64 v152, 0, v152, s[46:47]
	v_pk_add_f32 v[202:203], v[202:203], v[152:153] op_sel_hi:[1,0] neg_lo:[0,1] neg_hi:[0,1]
	v_pk_add_f32 v[204:205], v[204:205], v[152:153] op_sel_hi:[1,0] neg_lo:[0,1] neg_hi:[0,1]
	v_pk_add_f32 v[206:207], v[206:207], v[152:153] op_sel_hi:[1,0] neg_lo:[0,1] neg_hi:[0,1]
	v_pk_add_f32 v[208:209], v[208:209], v[152:153] op_sel_hi:[1,0] neg_lo:[0,1] neg_hi:[0,1]
	v_cndmask_b32_e64 v152, 1.0, v153, s[46:47]
	v_pk_mul_f32 v[202:203], v[152:153], v[202:203] op_sel_hi:[0,1]
	v_pk_mul_f32 v[204:205], v[152:153], v[204:205] op_sel_hi:[0,1]
	v_pk_mul_f32 v[206:207], v[152:153], v[206:207] op_sel_hi:[0,1]
	v_pk_mul_f32 v[208:209], v[152:153], v[208:209] op_sel_hi:[0,1]
	v_pk_fma_f32 v[202:203], v[144:145], v[202:203], v[156:157]
	v_pk_fma_f32 v[204:205], v[146:147], v[204:205], v[158:159]
	v_pk_fma_f32 v[206:207], v[148:149], v[206:207], v[170:171]
	v_pk_fma_f32 v[208:209], v[150:151], v[208:209], v[172:173]
	v_pk_fma_f32 v[94:95], v[138:139], v[94:95], v[202:203]
	v_pk_fma_f32 v[96:97], v[138:139], v[96:97], v[204:205]
	v_pk_fma_f32 v[90:91], v[138:139], v[90:91], v[206:207]
	v_pk_fma_f32 v[92:93], v[138:139], v[92:93], v[208:209]
	global_store_dwordx4 v180, v[94:97], s[40:41]
	global_store_dwordx4 v180, v[90:93], s[40:41] offset:16
	global_load_dwordx2 v[152:153], v179, s[96:97]
	global_load_dwordx4 v[202:205], v180, s[94:95] offset:512
	global_load_dwordx4 v[206:209], v180, s[94:95] offset:528
	s_waitcnt vmcnt(15)
	v_cndmask_b32_e64 v160, 0, v160, s[46:47]
	v_pk_add_f32 v[210:211], v[210:211], v[160:161] op_sel_hi:[1,0] neg_lo:[0,1] neg_hi:[0,1]
	v_pk_add_f32 v[212:213], v[212:213], v[160:161] op_sel_hi:[1,0] neg_lo:[0,1] neg_hi:[0,1]
	v_pk_add_f32 v[226:227], v[226:227], v[160:161] op_sel_hi:[1,0] neg_lo:[0,1] neg_hi:[0,1]
	v_pk_add_f32 v[228:229], v[228:229], v[160:161] op_sel_hi:[1,0] neg_lo:[0,1] neg_hi:[0,1]
	v_cndmask_b32_e64 v160, 1.0, v161, s[46:47]
	v_pk_mul_f32 v[210:211], v[160:161], v[210:211] op_sel_hi:[0,1]
	v_pk_mul_f32 v[212:213], v[160:161], v[212:213] op_sel_hi:[0,1]
	v_pk_mul_f32 v[226:227], v[160:161], v[226:227] op_sel_hi:[0,1]
	v_pk_mul_f32 v[228:229], v[160:161], v[228:229] op_sel_hi:[0,1]
	v_pk_fma_f32 v[210:211], v[144:145], v[210:211], v[156:157]
	v_pk_fma_f32 v[212:213], v[146:147], v[212:213], v[158:159]
	v_pk_fma_f32 v[226:227], v[148:149], v[226:227], v[170:171]
	v_pk_fma_f32 v[228:229], v[150:151], v[228:229], v[172:173]
	v_pk_fma_f32 v[86:87], v[138:139], v[86:87], v[210:211]
	v_pk_fma_f32 v[88:89], v[138:139], v[88:89], v[212:213]
	v_pk_fma_f32 v[82:83], v[138:139], v[82:83], v[226:227]
	v_pk_fma_f32 v[84:85], v[138:139], v[84:85], v[228:229]
	global_store_dwordx4 v182, v[86:89], s[40:41]
	global_store_dwordx4 v182, v[82:85], s[40:41] offset:16
	global_load_dwordx2 v[160:161], v179, s[96:97] offset:128
	global_load_dwordx4 v[210:213], v182, s[94:95] offset:512
	global_load_dwordx4 v[226:229], v182, s[94:95] offset:528
	s_waitcnt vmcnt(15)
	v_cndmask_b32_e64 v216, 0, v216, s[46:47]
	v_pk_add_f32 v[230:231], v[230:231], v[216:217] op_sel_hi:[1,0] neg_lo:[0,1] neg_hi:[0,1]
	v_pk_add_f32 v[232:233], v[232:233], v[216:217] op_sel_hi:[1,0] neg_lo:[0,1] neg_hi:[0,1]
	v_pk_add_f32 v[234:235], v[234:235], v[216:217] op_sel_hi:[1,0] neg_lo:[0,1] neg_hi:[0,1]
	v_pk_add_f32 v[236:237], v[236:237], v[216:217] op_sel_hi:[1,0] neg_lo:[0,1] neg_hi:[0,1]
	v_cndmask_b32_e64 v216, 1.0, v217, s[46:47]
	v_pk_mul_f32 v[230:231], v[216:217], v[230:231] op_sel_hi:[0,1]
	v_pk_mul_f32 v[232:233], v[216:217], v[232:233] op_sel_hi:[0,1]
	v_pk_mul_f32 v[234:235], v[216:217], v[234:235] op_sel_hi:[0,1]
	v_pk_mul_f32 v[236:237], v[216:217], v[236:237] op_sel_hi:[0,1]
	v_pk_fma_f32 v[230:231], v[144:145], v[230:231], v[156:157]
	v_pk_fma_f32 v[232:233], v[146:147], v[232:233], v[158:159]
	v_pk_fma_f32 v[234:235], v[148:149], v[234:235], v[170:171]
	v_pk_fma_f32 v[236:237], v[150:151], v[236:237], v[172:173]
	v_pk_fma_f32 v[78:79], v[138:139], v[78:79], v[230:231]
	v_pk_fma_f32 v[80:81], v[138:139], v[80:81], v[232:233]
	v_pk_fma_f32 v[74:75], v[138:139], v[74:75], v[234:235]
	v_pk_fma_f32 v[76:77], v[138:139], v[76:77], v[236:237]
	global_store_dwordx4 v183, v[78:81], s[40:41]
	global_store_dwordx4 v183, v[74:77], s[40:41] offset:16
	global_load_dwordx2 v[216:217], v179, s[96:97] offset:256
	global_load_dwordx4 v[230:233], v183, s[94:95] offset:512
	global_load_dwordx4 v[234:237], v183, s[94:95] offset:528
	s_waitcnt vmcnt(15)
	v_cndmask_b32_e64 v246, 0, v246, s[46:47]
	v_pk_add_f32 v[238:239], v[238:239], v[246:247] op_sel_hi:[1,0] neg_lo:[0,1] neg_hi:[0,1]
	v_pk_add_f32 v[240:241], v[240:241], v[246:247] op_sel_hi:[1,0] neg_lo:[0,1] neg_hi:[0,1]
	v_pk_add_f32 v[242:243], v[242:243], v[246:247] op_sel_hi:[1,0] neg_lo:[0,1] neg_hi:[0,1]
	v_pk_add_f32 v[244:245], v[244:245], v[246:247] op_sel_hi:[1,0] neg_lo:[0,1] neg_hi:[0,1]
	v_cndmask_b32_e64 v246, 1.0, v247, s[46:47]
	v_pk_mul_f32 v[238:239], v[246:247], v[238:239] op_sel_hi:[0,1]
	v_pk_mul_f32 v[240:241], v[246:247], v[240:241] op_sel_hi:[0,1]
	v_pk_mul_f32 v[242:243], v[246:247], v[242:243] op_sel_hi:[0,1]
	v_pk_mul_f32 v[244:245], v[246:247], v[244:245] op_sel_hi:[0,1]
	v_pk_fma_f32 v[238:239], v[144:145], v[238:239], v[156:157]
	v_pk_fma_f32 v[240:241], v[146:147], v[240:241], v[158:159]
	v_pk_fma_f32 v[242:243], v[148:149], v[242:243], v[170:171]
	v_pk_fma_f32 v[244:245], v[150:151], v[244:245], v[172:173]
	v_pk_fma_f32 v[70:71], v[138:139], v[70:71], v[238:239]
	v_pk_fma_f32 v[72:73], v[138:139], v[72:73], v[240:241]
	v_pk_fma_f32 v[66:67], v[138:139], v[66:67], v[242:243]
	v_pk_fma_f32 v[68:69], v[138:139], v[68:69], v[244:245]
	global_store_dwordx4 v184, v[70:73], s[40:41]
	global_store_dwordx4 v184, v[66:69], s[40:41] offset:16
	global_load_dwordx2 v[246:247], v179, s[96:97] offset:384
	global_load_dwordx4 v[238:241], v184, s[94:95] offset:512
	global_load_dwordx4 v[242:245], v184, s[94:95] offset:528
	s_waitcnt vmcnt(15)
;     __device__ __forceinline__ void operator()(const f32x4 (&acc)[2][2][4][2], const Unit& u, int wr, int wc, int fr, int fq) const {
;     ...
;         for (int bj = 0; bj < 2; ++bj) {
;             const int c = col0 + bj * 128;
;             f32x4 g0 = {1.f, 1.f, 1.f, 1.f}, g1 = g0, b0 = {0.f, 0.f, 0.f, 0.f}, b1 = b0;
;             if (lng) { g0 = *(const f32x4*)(lng + c); g1 = *(const f32x4*)(lng + c + 4); b0 = *(const f32x4*)(lnb + c); b1 = *(const f32x4*)(lnb + c + 4); }
;             g0 = g0 * ca; g1 = g1 * ca; b0 = b0 * ca; b1 = b1 * ca;
; #pragma unroll
;             for (int ai = 0; ai < 2; ++ai)
; #pragma unroll
;                 for (int m = 0; m < 4; ++m) {
;                     const int row = row0 + ai * 128 + m * 16;
;                     float mean = 0.f, rstd = 1.f;
;                     if (lng) { const float2 st = *(const float2*)(stats + 2 * (size_t)row); mean = st.x; rstd = st.y; }
;                     float* p = X + (size_t)row * DM + c;
;                     f32x4 x0 = *(const f32x4*)p, x1 = *(const f32x4*)(p + 4);
;                     x0 = (x0 - mean) * rstd * g0 + b0 + acc[ai][bj][m][0] * cb; x1 = (x1 - mean) * rstd * g1 + b1 + acc[ai][bj][m][1] * cb;
;                     *(f32x4*)p = x0; *(f32x4*)(p + 4) = x1;
;                     if (m & 1) asm volatile("" ::: "memory");
;                 }
	v_cndmask_b32_e64 v152, 0, v152, s[46:47]
	v_pk_add_f32 v[202:203], v[202:203], v[152:153] op_sel_hi:[1,0] neg_lo:[0,1] neg_hi:[0,1]
	v_pk_add_f32 v[204:205], v[204:205], v[152:153] op_sel_hi:[1,0] neg_lo:[0,1] neg_hi:[0,1]
	v_pk_add_f32 v[206:207], v[206:207], v[152:153] op_sel_hi:[1,0] neg_lo:[0,1] neg_hi:[0,1]
	v_pk_add_f32 v[208:209], v[208:209], v[152:153] op_sel_hi:[1,0] neg_lo:[0,1] neg_hi:[0,1]
	v_cndmask_b32_e64 v152, 1.0, v153, s[46:47]
	v_pk_mul_f32 v[202:203], v[152:153], v[202:203] op_sel_hi:[0,1]
	v_pk_mul_f32 v[204:205], v[152:153], v[204:205] op_sel_hi:[0,1]
	v_pk_mul_f32 v[206:207], v[152:153], v[206:207] op_sel_hi:[0,1]
	v_pk_mul_f32 v[208:209], v[152:153], v[208:209] op_sel_hi:[0,1]
	v_pk_fma_f32 v[202:203], v[174:175], v[202:203], v[194:195]
	v_pk_fma_f32 v[204:205], v[176:177], v[204:205], v[196:197]
	v_pk_fma_f32 v[206:207], v[188:189], v[206:207], v[198:199]
	v_pk_fma_f32 v[208:209], v[190:191], v[208:209], v[200:201]
	v_pk_fma_f32 v[62:63], v[138:139], v[62:63], v[202:203]
	v_pk_fma_f32 v[64:65], v[138:139], v[64:65], v[204:205]
	v_pk_fma_f32 v[58:59], v[138:139], v[58:59], v[206:207]
	v_pk_fma_f32 v[60:61], v[138:139], v[60:61], v[208:209]
	global_store_dwordx4 v180, v[62:65], s[94:95] offset:512
	global_store_dwordx4 v180, v[58:61], s[94:95] offset:528
	global_load_dwordx2 v[152:153], v179, s[96:97] offset:1024
	global_load_dwordx4 v[202:205], v180, s[40:41] offset:512
	global_load_dwordx4 v[206:209], v180, s[40:41] offset:528
	s_waitcnt vmcnt(15)
	v_cndmask_b32_e64 v160, 0, v160, s[46:47]
	v_pk_add_f32 v[210:211], v[210:211], v[160:161] op_sel_hi:[1,0] neg_lo:[0,1] neg_hi:[0,1]
	v_pk_add_f32 v[212:213], v[212:213], v[160:161] op_sel_hi:[1,0] neg_lo:[0,1] neg_hi:[0,1]
	v_pk_add_f32 v[226:227], v[226:227], v[160:161] op_sel_hi:[1,0] neg_lo:[0,1] neg_hi:[0,1]
	v_pk_add_f32 v[228:229], v[228:229], v[160:161] op_sel_hi:[1,0] neg_lo:[0,1] neg_hi:[0,1]
	v_cndmask_b32_e64 v160, 1.0, v161, s[46:47]
	v_pk_mul_f32 v[210:211], v[160:161], v[210:211] op_sel_hi:[0,1]
	v_pk_mul_f32 v[212:213], v[160:161], v[212:213] op_sel_hi:[0,1]
	v_pk_mul_f32 v[226:227], v[160:161], v[226:227] op_sel_hi:[0,1]
	v_pk_mul_f32 v[228:229], v[160:161], v[228:229] op_sel_hi:[0,1]
	v_pk_fma_f32 v[210:211], v[174:175], v[210:211], v[194:195]
	v_pk_fma_f32 v[212:213], v[176:177], v[212:213], v[196:197]
	v_pk_fma_f32 v[226:227], v[188:189], v[226:227], v[198:199]
	v_pk_fma_f32 v[228:229], v[190:191], v[228:229], v[200:201]
	v_pk_fma_f32 v[54:55], v[138:139], v[54:55], v[210:211]
	v_pk_fma_f32 v[56:57], v[138:139], v[56:57], v[212:213]
	v_pk_fma_f32 v[50:51], v[138:139], v[50:51], v[226:227]
	v_pk_fma_f32 v[52:53], v[138:139], v[52:53], v[228:229]
	global_store_dwordx4 v182, v[54:57], s[94:95] offset:512
	global_store_dwordx4 v182, v[50:53], s[94:95] offset:528
	global_load_dwordx2 v[160:161], v179, s[96:97] offset:1152
	global_load_dwordx4 v[210:213], v182, s[40:41] offset:512
	global_load_dwordx4 v[226:229], v182, s[40:41] offset:528
	s_waitcnt vmcnt(15)
	v_cndmask_b32_e64 v216, 0, v216, s[46:47]
	v_pk_add_f32 v[230:231], v[230:231], v[216:217] op_sel_hi:[1,0] neg_lo:[0,1] neg_hi:[0,1]
	v_pk_add_f32 v[232:233], v[232:233], v[216:217] op_sel_hi:[1,0] neg_lo:[0,1] neg_hi:[0,1]
	v_pk_add_f32 v[234:235], v[234:235], v[216:217] op_sel_hi:[1,0] neg_lo:[0,1] neg_hi:[0,1]
	v_pk_add_f32 v[236:237], v[236:237], v[216:217] op_sel_hi:[1,0] neg_lo:[0,1] neg_hi:[0,1]
	v_cndmask_b32_e64 v216, 1.0, v217, s[46:47]
	v_pk_mul_f32 v[230:231], v[216:217], v[230:231] op_sel_hi:[0,1]
	v_pk_mul_f32 v[232:233], v[216:217], v[232:233] op_sel_hi:[0,1]
	v_pk_mul_f32 v[234:235], v[216:217], v[234:235] op_sel_hi:[0,1]
	v_pk_mul_f32 v[236:237], v[216:217], v[236:237] op_sel_hi:[0,1]
	v_pk_fma_f32 v[230:231], v[174:175], v[230:231], v[194:195]
	v_pk_fma_f32 v[232:233], v[176:177], v[232:233], v[196:197]
	v_pk_fma_f32 v[234:235], v[188:189], v[234:235], v[198:199]
	v_pk_fma_f32 v[236:237], v[190:191], v[236:237], v[200:201]
	v_pk_fma_f32 v[46:47], v[138:139], v[46:47], v[230:231]
	v_pk_fma_f32 v[48:49], v[138:139], v[48:49], v[232:233]
	v_pk_fma_f32 v[42:43], v[138:139], v[42:43], v[234:235]
	v_pk_fma_f32 v[44:45], v[138:139], v[44:45], v[236:237]
	global_store_dwordx4 v183, v[46:49], s[94:95] offset:512
	global_store_dwordx4 v183, v[42:45], s[94:95] offset:528
	global_load_dwordx2 v[216:217], v179, s[96:97] offset:1280
	global_load_dwordx4 v[230:233], v183, s[40:41] offset:512
	global_load_dwordx4 v[234:237], v183, s[40:41] offset:528
	s_waitcnt vmcnt(15)
	v_cndmask_b32_e64 v246, 0, v246, s[46:47]
	v_pk_add_f32 v[238:239], v[238:239], v[246:247] op_sel_hi:[1,0] neg_lo:[0,1] neg_hi:[0,1]
	v_pk_add_f32 v[240:241], v[240:241], v[246:247] op_sel_hi:[1,0] neg_lo:[0,1] neg_hi:[0,1]
	v_pk_add_f32 v[242:243], v[242:243], v[246:247] op_sel_hi:[1,0] neg_lo:[0,1] neg_hi:[0,1]
	v_pk_add_f32 v[244:245], v[244:245], v[246:247] op_sel_hi:[1,0] neg_lo:[0,1] neg_hi:[0,1]
	v_cndmask_b32_e64 v246, 1.0, v247, s[46:47]
	v_pk_mul_f32 v[238:239], v[246:247], v[238:239] op_sel_hi:[0,1]
	v_pk_mul_f32 v[240:241], v[246:247], v[240:241] op_sel_hi:[0,1]
	v_pk_mul_f32 v[242:243], v[246:247], v[242:243] op_sel_hi:[0,1]
	v_pk_mul_f32 v[244:245], v[246:247], v[244:245] op_sel_hi:[0,1]
	v_pk_fma_f32 v[238:239], v[174:175], v[238:239], v[194:195]
	v_pk_fma_f32 v[240:241], v[176:177], v[240:241], v[196:197]
	v_pk_fma_f32 v[242:243], v[188:189], v[242:243], v[198:199]
	v_pk_fma_f32 v[244:245], v[190:191], v[244:245], v[200:201]
	v_pk_fma_f32 v[38:39], v[138:139], v[38:39], v[238:239]
	v_pk_fma_f32 v[40:41], v[138:139], v[40:41], v[240:241]
	v_pk_fma_f32 v[34:35], v[138:139], v[34:35], v[242:243]
	v_pk_fma_f32 v[36:37], v[138:139], v[36:37], v[244:245]
	global_store_dwordx4 v184, v[38:41], s[94:95] offset:512
	global_store_dwordx4 v184, v[34:37], s[94:95] offset:528
	global_load_dwordx2 v[246:247], v179, s[96:97] offset:1408
	global_load_dwordx4 v[238:241], v184, s[40:41] offset:512
	global_load_dwordx4 v[242:245], v184, s[40:41] offset:528
	s_waitcnt vmcnt(15)
;     __device__ __forceinline__ void operator()(const f32x4 (&acc)[2][2][4][2], const Unit& u, int wr, int wc, int fr, int fq) const {
;     ...
;         for (int bj = 0; bj < 2; ++bj) {
;             const int c = col0 + bj * 128;
;             f32x4 g0 = {1.f, 1.f, 1.f, 1.f}, g1 = g0, b0 = {0.f, 0.f, 0.f, 0.f}, b1 = b0;
;             if (lng) { g0 = *(const f32x4*)(lng + c); g1 = *(const f32x4*)(lng + c + 4); b0 = *(const f32x4*)(lnb + c); b1 = *(const f32x4*)(lnb + c + 4); }
;             g0 = g0 * ca; g1 = g1 * ca; b0 = b0 * ca; b1 = b1 * ca;
; #pragma unroll
;             for (int ai = 0; ai < 2; ++ai)
; #pragma unroll
;                 for (int m = 0; m < 4; ++m) {
;                     const int row = row0 + ai * 128 + m * 16;
;                     float mean = 0.f, rstd = 1.f;
;                     if (lng) { const float2 st = *(const float2*)(stats + 2 * (size_t)row); mean = st.x; rstd = st.y; }
;                     float* p = X + (size_t)row * DM + c;
;                     f32x4 x0 = *(const f32x4*)p, x1 = *(const f32x4*)(p + 4);
;                     x0 = (x0 - mean) * rstd * g0 + b0 + acc[ai][bj][m][0] * cb; x1 = (x1 - mean) * rstd * g1 + b1 + acc[ai][bj][m][1] * cb;
;                     *(f32x4*)p = x0; *(f32x4*)(p + 4) = x1;
;                     if (m & 1) asm volatile("" ::: "memory");
;                 }
	v_cndmask_b32_e64 v152, 0, v152, s[46:47]
	v_pk_add_f32 v[202:203], v[202:203], v[152:153] op_sel_hi:[1,0] neg_lo:[0,1] neg_hi:[0,1]
	v_pk_add_f32 v[204:205], v[204:205], v[152:153] op_sel_hi:[1,0] neg_lo:[0,1] neg_hi:[0,1]
	v_pk_add_f32 v[206:207], v[206:207], v[152:153] op_sel_hi:[1,0] neg_lo:[0,1] neg_hi:[0,1]
	v_pk_add_f32 v[208:209], v[208:209], v[152:153] op_sel_hi:[1,0] neg_lo:[0,1] neg_hi:[0,1]
	v_cndmask_b32_e64 v152, 1.0, v153, s[46:47]
	v_pk_mul_f32 v[202:203], v[152:153], v[202:203] op_sel_hi:[0,1]
	v_pk_mul_f32 v[204:205], v[152:153], v[204:205] op_sel_hi:[0,1]
	v_pk_mul_f32 v[206:207], v[152:153], v[206:207] op_sel_hi:[0,1]
	v_pk_mul_f32 v[208:209], v[152:153], v[208:209] op_sel_hi:[0,1]
	v_pk_fma_f32 v[202:203], v[174:175], v[202:203], v[194:195]
	v_pk_fma_f32 v[204:205], v[176:177], v[204:205], v[196:197]
	v_pk_fma_f32 v[206:207], v[188:189], v[206:207], v[198:199]
	v_pk_fma_f32 v[208:209], v[190:191], v[208:209], v[200:201]
	v_pk_fma_f32 v[30:31], v[138:139], v[30:31], v[202:203]
	v_pk_fma_f32 v[32:33], v[138:139], v[32:33], v[204:205]
	v_pk_fma_f32 v[26:27], v[138:139], v[26:27], v[206:207]
	v_pk_fma_f32 v[28:29], v[138:139], v[28:29], v[208:209]
	global_store_dwordx4 v180, v[30:33], s[40:41] offset:512
	global_store_dwordx4 v180, v[26:29], s[40:41] offset:528
	s_waitcnt vmcnt(12)
	v_cndmask_b32_e64 v160, 0, v160, s[46:47]
	v_pk_add_f32 v[210:211], v[210:211], v[160:161] op_sel_hi:[1,0] neg_lo:[0,1] neg_hi:[0,1]
	v_pk_add_f32 v[212:213], v[212:213], v[160:161] op_sel_hi:[1,0] neg_lo:[0,1] neg_hi:[0,1]
	v_pk_add_f32 v[226:227], v[226:227], v[160:161] op_sel_hi:[1,0] neg_lo:[0,1] neg_hi:[0,1]
	v_pk_add_f32 v[228:229], v[228:229], v[160:161] op_sel_hi:[1,0] neg_lo:[0,1] neg_hi:[0,1]
	v_cndmask_b32_e64 v160, 1.0, v161, s[46:47]
	v_pk_mul_f32 v[210:211], v[160:161], v[210:211] op_sel_hi:[0,1]
	v_pk_mul_f32 v[212:213], v[160:161], v[212:213] op_sel_hi:[0,1]
	v_pk_mul_f32 v[226:227], v[160:161], v[226:227] op_sel_hi:[0,1]
	v_pk_mul_f32 v[228:229], v[160:161], v[228:229] op_sel_hi:[0,1]
	v_pk_fma_f32 v[210:211], v[174:175], v[210:211], v[194:195]
	v_pk_fma_f32 v[212:213], v[176:177], v[212:213], v[196:197]
	v_pk_fma_f32 v[226:227], v[188:189], v[226:227], v[198:199]
	v_pk_fma_f32 v[228:229], v[190:191], v[228:229], v[200:201]
	v_pk_fma_f32 v[22:23], v[138:139], v[22:23], v[210:211]
	v_pk_fma_f32 v[24:25], v[138:139], v[24:25], v[212:213]
	v_pk_fma_f32 v[18:19], v[138:139], v[18:19], v[226:227]
	v_pk_fma_f32 v[20:21], v[138:139], v[20:21], v[228:229]
	global_store_dwordx4 v182, v[22:25], s[40:41] offset:512
	global_store_dwordx4 v182, v[18:21], s[40:41] offset:528
	s_waitcnt vmcnt(9)
	v_cndmask_b32_e64 v216, 0, v216, s[46:47]
	v_pk_add_f32 v[230:231], v[230:231], v[216:217] op_sel_hi:[1,0] neg_lo:[0,1] neg_hi:[0,1]
	v_pk_add_f32 v[232:233], v[232:233], v[216:217] op_sel_hi:[1,0] neg_lo:[0,1] neg_hi:[0,1]
	v_pk_add_f32 v[234:235], v[234:235], v[216:217] op_sel_hi:[1,0] neg_lo:[0,1] neg_hi:[0,1]
	v_pk_add_f32 v[236:237], v[236:237], v[216:217] op_sel_hi:[1,0] neg_lo:[0,1] neg_hi:[0,1]
	v_cndmask_b32_e64 v216, 1.0, v217, s[46:47]
	v_pk_mul_f32 v[230:231], v[216:217], v[230:231] op_sel_hi:[0,1]
	v_pk_mul_f32 v[232:233], v[216:217], v[232:233] op_sel_hi:[0,1]
	v_pk_mul_f32 v[234:235], v[216:217], v[234:235] op_sel_hi:[0,1]
	v_pk_mul_f32 v[236:237], v[216:217], v[236:237] op_sel_hi:[0,1]
	v_pk_fma_f32 v[230:231], v[174:175], v[230:231], v[194:195]
	v_pk_fma_f32 v[232:233], v[176:177], v[232:233], v[196:197]
	v_pk_fma_f32 v[234:235], v[188:189], v[234:235], v[198:199]
	v_pk_fma_f32 v[236:237], v[190:191], v[236:237], v[200:201]
	v_pk_fma_f32 v[14:15], v[138:139], v[14:15], v[230:231]
	v_pk_fma_f32 v[16:17], v[138:139], v[16:17], v[232:233]
	v_pk_fma_f32 v[10:11], v[138:139], v[10:11], v[234:235]
	v_pk_fma_f32 v[12:13], v[138:139], v[12:13], v[236:237]
	global_store_dwordx4 v183, v[14:17], s[40:41] offset:512
	global_store_dwordx4 v183, v[10:13], s[40:41] offset:528
	s_waitcnt vmcnt(6)
	v_cndmask_b32_e64 v246, 0, v246, s[46:47]
	v_pk_add_f32 v[238:239], v[238:239], v[246:247] op_sel_hi:[1,0] neg_lo:[0,1] neg_hi:[0,1]
	v_pk_add_f32 v[240:241], v[240:241], v[246:247] op_sel_hi:[1,0] neg_lo:[0,1] neg_hi:[0,1]
	v_pk_add_f32 v[242:243], v[242:243], v[246:247] op_sel_hi:[1,0] neg_lo:[0,1] neg_hi:[0,1]
	v_pk_add_f32 v[244:245], v[244:245], v[246:247] op_sel_hi:[1,0] neg_lo:[0,1] neg_hi:[0,1]
	v_cndmask_b32_e64 v246, 1.0, v247, s[46:47]
	v_pk_mul_f32 v[238:239], v[246:247], v[238:239] op_sel_hi:[0,1]
	v_pk_mul_f32 v[240:241], v[246:247], v[240:241] op_sel_hi:[0,1]
	v_pk_mul_f32 v[242:243], v[246:247], v[242:243] op_sel_hi:[0,1]
	v_pk_mul_f32 v[244:245], v[246:247], v[244:245] op_sel_hi:[0,1]
	v_pk_fma_f32 v[238:239], v[174:175], v[238:239], v[194:195]
	v_pk_fma_f32 v[240:241], v[176:177], v[240:241], v[196:197]
	v_pk_fma_f32 v[242:243], v[188:189], v[242:243], v[198:199]
	v_pk_fma_f32 v[244:245], v[190:191], v[244:245], v[200:201]
	v_pk_fma_f32 v[6:7], v[138:139], v[6:7], v[238:239]
	v_pk_fma_f32 v[8:9], v[138:139], v[8:9], v[240:241]
	v_pk_fma_f32 v[2:3], v[138:139], v[2:3], v[242:243]
	v_pk_fma_f32 v[4:5], v[138:139], v[4:5], v[244:245]
	global_store_dwordx4 v184, v[6:9], s[40:41] offset:512
	global_store_dwordx4 v184, v[2:5], s[40:41] offset:528
	s_and_b64 vcc, exec, s[38:39]
	s_mov_b64 s[6:7], -1
	s_cbranch_vccnz .LBB0_805
	s_andn2_b64 vcc, exec, s[26:27]
	s_cbranch_vccnz .LBB0_804
	s_barrier
	s_branch .LBB0_804

; __global__ void __launch_bounds__(NT, 2) mk_fwd(Params P) {
;     __shared__ __attribute__((aligned(16))) unsigned char lds_raw[LDS_BYTES];
	.amdhsa_kernel _ZN2mk6mk_fwdENS_6ParamsE
		.amdhsa_group_segment_fixed_size 147456
		.amdhsa_private_segment_fixed_size 0
		.amdhsa_kernarg_size 488
		.amdhsa_user_sgpr_count 2
		.amdhsa_user_sgpr_dispatch_ptr 0
		.amdhsa_user_sgpr_queue_ptr 0
		.amdhsa_user_sgpr_kernarg_segment_ptr 1
		.amdhsa_user_sgpr_dispatch_id 0
		.amdhsa_user_sgpr_kernarg_preload_length 0
		.amdhsa_user_sgpr_kernarg_preload_offset 0
		.amdhsa_user_sgpr_private_segment_size 0
		.amdhsa_uses_dynamic_stack 0
		.amdhsa_enable_private_segment 0
		.amdhsa_system_sgpr_workgroup_id_x 1
		.amdhsa_system_sgpr_workgroup_id_y 0
		.amdhsa_system_sgpr_workgroup_id_z 0
		.amdhsa_system_sgpr_workgroup_info 0
		.amdhsa_system_vgpr_workitem_id 2
		.amdhsa_next_free_vgpr 256
		.amdhsa_next_free_sgpr 102
		.amdhsa_accum_offset 256
		.amdhsa_reserve_vcc 1
		.amdhsa_float_round_mode_32 0
		.amdhsa_float_round_mode_16_64 0
		.amdhsa_float_denorm_mode_32 3
		.amdhsa_float_denorm_mode_16_64 3
		.amdhsa_dx10_clamp 1
		.amdhsa_ieee_mode 1
		.amdhsa_fp16_overflow 0
		.amdhsa_tg_split 0
		.amdhsa_exception_fp_ieee_invalid_op 0
		.amdhsa_exception_fp_denorm_src 0
		.amdhsa_exception_fp_ieee_div_zero 0
		.amdhsa_exception_fp_ieee_overflow 0
		.amdhsa_exception_fp_ieee_underflow 0
		.amdhsa_exception_fp_ieee_inexact 0
		.amdhsa_exception_int_div_zero 0
	.end_amdhsa_kernel

; __global__ void __launch_bounds__(NT, 2) mk_fwd(Params P) {
;     __shared__ __attribute__((aligned(16))) unsigned char lds_raw[LDS_BYTES];
amdhsa.kernels:
  - .agpr_count:     0
    .args:
      - .offset:         0
        .size:           232
        .value_kind:     by_value
      - .offset:         232
        .size:           4
        .value_kind:     hidden_block_count_x
      - .offset:         236
        .size:           4
        .value_kind:     hidden_block_count_y
      - .offset:         240
        .size:           4
        .value_kind:     hidden_block_count_z
      - .offset:         244
        .size:           2
        .value_kind:     hidden_group_size_x
      - .offset:         246
        .size:           2
        .value_kind:     hidden_group_size_y
      - .offset:         248
        .size:           2
        .value_kind:     hidden_group_size_z
      - .offset:         250
        .size:           2
        .value_kind:     hidden_remainder_x
      - .offset:         252
        .size:           2
        .value_kind:     hidden_remainder_y
      - .offset:         254
        .size:           2
        .value_kind:     hidden_remainder_z
      - .offset:         272
        .size:           8
        .value_kind:     hidden_global_offset_x
      - .offset:         280
        .size:           8
        .value_kind:     hidden_global_offset_y
      - .offset:         288
        .size:           8
        .value_kind:     hidden_global_offset_z
      - .offset:         296
        .size:           2
        .value_kind:     hidden_grid_dims
      - .offset:         320
        .size:           8
        .value_kind:     hidden_multigrid_sync_arg
    .group_segment_fixed_size: 147456
    .kernarg_segment_align: 8
    .kernarg_segment_size: 488
    .language:       OpenCL C
    .language_version:
      - 2
      - 0
    .max_flat_workgroup_size: 512
    .name:           _ZN2mk6mk_fwdENS_6ParamsE
    .private_segment_fixed_size: 0
    .sgpr_count:     108
    .sgpr_spill_count: 261
    .symbol:         _ZN2mk6mk_fwdENS_6ParamsE.kd
    .uniform_work_group_size: 1
    .uses_dynamic_stack: false
    .vgpr_count:     256
    .vgpr_spill_count: 0
    .wavefront_size: 64
